# out-projection and merge tile epilogues: residual/gate loads issued together with counted waits; part-B queue pull prefetches the next tile index while the queue is far from empty
# speedup vs baseline: 1.0051x; 1.0051x over previous
; __device__ void ph_scan(const Params& p, int l, int g, char* smem) {
;     ...
;   for (int it = 0;; ++it) {
;     if (threadIdx.x == 0) tb_s[it & 1] = (int)atomicAdd(ctr, 1u);
;     __syncthreads();
;     const int tb = tb_s[it & 1];
;     if (tb >= QB_END) break;
;     gemm_in_b_tile(p, l, smem, tb);
.LBB0_719:
	s_and_b32 s40, s50, 1
	s_mov_b64 s[38:39], exec
	v_readlane_b32 s42, v242, 5
	v_readlane_b32 s43, v242, 6
	s_and_b64 s[42:43], s[38:39], s[42:43]
	s_mov_b64 exec, s[42:43]
	s_cbranch_execz .LBB0_721
	s_cmp_lg_u32 s50, 0
	s_cbranch_scc1 .Lpf_notfirst
	s_mov_b32 s101, 0
.Lpf_notfirst:
	s_bitcmp1_b32 s101, 0
	s_cbranch_scc1 .Lpf_have
	global_atomic_add v254, v[134:135], v167, off sc0
	s_mov_b32 s101, 1
.Lpf_have:
	s_bitcmp1_b32 s101, 1
	s_cbranch_scc1 .Lpf_ready
	s_waitcnt vmcnt(0)
.Lpf_ready:
	v_mov_b32_e32 v0, v254
	s_mov_b32 s101, 0
	v_readfirstlane_b32 s41, v0
	s_cmpk_lt_u32 s41, 0x500
	s_cbranch_scc0 .Lpf_nopf
	global_atomic_add v254, v[134:135], v167, off sc0
	s_mov_b32 s101, 1
.Lpf_nopf:
	s_lshl_b32 s41, s40, 2
	s_or_b32 s41, s41, 0x12210
	v_mov_b32_e32 v2, s41
	ds_write_b32 v2, v0

; template <int MF, int NF>
; __device__ __forceinline__ void gemm_kloopT(const u16* Ag, long lda, long aks, const u16* Bg, long ldb, long bks, int K, char* smem, f32x4 (&acc)[MF][NF]) {
;     ...
;   GK_ISSUE(0, 0)
;   GK_ISSUE(1, 1)
;   const int co = (fq ^ (((fr >> 3) & 1) << 1)) * 16;
;     ...
;   const unsigned lds0 = (unsigned)(unsigned long)(__attribute__((address_space(3))) const char*)smem;
;   const unsigned aA = lds0 + (wr * MF * 16 + fr) * 64 + co;
;   const unsigned aB = lds0 + ASZ + (wc * NF * 16 + fr) * 64 + co;
;   for (int t = 0; t < nt - 2; t += 3) {
;     GK_STEP(t, 0, 2, false, false)
;     GK_STEP(t + 1, 1, 0, false, false)
;     GK_STEP(t + 2, 2, 1, false, false)
;   }
;   GK_STEP(nt - 2, 0, 2, false, true)
;   GK_STEP(nt - 1, 1, 0, true, true)
.LBB0_725:
	v_add_u32_e32 v84, 0x8000, v74
	v_lshl_add_u64 v[70:71], v[68:69], 0, v[0:1]
	v_readfirstlane_b32 s39, v84
	v_add_u32_e32 v84, 0x9000, v74
	v_lshl_add_u64 v[72:73], v[70:71], 0, s[16:17]
	s_mov_b32 m0, s39
	v_readfirstlane_b32 s39, v84
	s_waitcnt vmcnt(4)
	s_barrier
	global_load_lds_dwordx4 v[72:73], off
	v_lshl_add_u64 v[72:73], v[70:71], 0, s[12:13]
	s_mov_b32 m0, s39
	v_add_u32_e32 v86, 0xa000, v74
	global_load_lds_dwordx4 v[72:73], off
	v_lshl_add_u64 v[72:73], v[66:67], 0, v[0:1]
	v_readfirstlane_b32 s39, v86
	v_add_u32_e32 v86, 0xb000, v74
	v_lshl_add_u64 v[84:85], v[72:73], 0, s[28:29]
	s_mov_b32 m0, s39
	v_readfirstlane_b32 s39, v86
	global_load_lds_dwordx4 v[84:85], off
	v_lshl_add_u64 v[84:85], v[72:73], 0, s[30:31]
	s_mov_b32 m0, s39
	v_readfirstlane_b32 s39, v74
	global_load_lds_dwordx4 v[84:85], off
	ds_read_b128 v[84:87], v76 offset:0
	ds_read_b128 v[88:91], v76 offset:0x400
	ds_read_b128 v[92:95], v76 offset:0x800
	ds_read_b128 v[96:99], v76 offset:0xc00
	ds_read_b128 v[100:103], v77 offset:0
	ds_read_b128 v[104:107], v77 offset:0x400
	ds_read_b128 v[108:111], v77 offset:0x800
	ds_read_b128 v[112:115], v77 offset:0xc00
	s_mov_b32 m0, s39
	s_waitcnt lgkmcnt(0)
	v_readfirstlane_b32 s39, v75
	v_mfma_f32_16x16x32_bf16 v[62:65], v[100:103], v[84:87], v[62:65]
	s_waitcnt vmcnt(4)
	s_barrier
	s_add_i32 s38, s38, 3
	v_mfma_f32_16x16x32_bf16 v[58:61], v[104:107], v[84:87], v[58:61]
	v_lshl_add_u64 v[66:67], v[66:67], 0, s[6:7]
	v_lshl_add_u64 v[68:69], v[68:69], 0, s[34:35]
	s_cmp_lt_u32 s38, 27
	v_mfma_f32_16x16x32_bf16 v[54:57], v[108:111], v[84:87], v[54:57]
	v_mfma_f32_16x16x32_bf16 v[50:53], v[112:115], v[84:87], v[50:53]
	v_lshl_add_u64 v[84:85], v[70:71], 0, s[34:35]
	global_load_lds_dwordx4 v[84:85], off
	v_lshl_add_u64 v[84:85], v[70:71], 0, s[36:37]
	s_mov_b32 m0, s39
	v_readfirstlane_b32 s39, v78
	global_load_lds_dwordx4 v[84:85], off
	v_lshl_add_u64 v[84:85], v[72:73], 0, s[6:7]
	s_mov_b32 m0, s39
	v_readfirstlane_b32 s39, v79
	global_load_lds_dwordx4 v[84:85], off
	v_lshl_add_u64 v[84:85], v[72:73], 0, s[0:1]
	s_mov_b32 m0, s39
	v_mfma_f32_16x16x32_bf16 v[46:49], v[100:103], v[88:91], v[46:49]
	global_load_lds_dwordx4 v[84:85], off
	ds_read_b128 v[84:87], v76 offset:0x4000
	v_mfma_f32_16x16x32_bf16 v[42:45], v[104:107], v[88:91], v[42:45]
	v_readfirstlane_b32 s39, v80
	s_mov_b32 m0, s39
	v_readfirstlane_b32 s39, v81
	v_mfma_f32_16x16x32_bf16 v[38:41], v[108:111], v[88:91], v[38:41]
	v_mfma_f32_16x16x32_bf16 v[34:37], v[112:115], v[88:91], v[34:37]
	ds_read_b128 v[88:91], v76 offset:0x4400
	v_mfma_f32_16x16x32_bf16 v[30:33], v[100:103], v[92:95], v[30:33]
	v_mfma_f32_16x16x32_bf16 v[26:29], v[104:107], v[92:95], v[26:29]
	v_mfma_f32_16x16x32_bf16 v[22:25], v[108:111], v[92:95], v[22:25]
	v_mfma_f32_16x16x32_bf16 v[18:21], v[112:115], v[92:95], v[18:21]
	ds_read_b128 v[92:95], v76 offset:0x4800
	v_mfma_f32_16x16x32_bf16 v[14:17], v[100:103], v[96:99], v[14:17]
	v_mfma_f32_16x16x32_bf16 v[10:13], v[104:107], v[96:99], v[10:13]
	v_mfma_f32_16x16x32_bf16 v[6:9], v[108:111], v[96:99], v[6:9]
	v_mfma_f32_16x16x32_bf16 v[2:5], v[112:115], v[96:99], v[2:5]
	ds_read_b128 v[96:99], v76 offset:0x4c00
	ds_read_b128 v[100:103], v77 offset:0x4000
	ds_read_b128 v[104:107], v77 offset:0x4400
	ds_read_b128 v[108:111], v77 offset:0x4800
	ds_read_b128 v[112:115], v77 offset:0x4c00
	s_nop 0
	s_waitcnt lgkmcnt(0)
	s_waitcnt vmcnt(4)
	s_barrier
; template <int MF, int NF>
; __device__ __forceinline__ void gemm_kloopT(const u16* Ag, long lda, long aks, const u16* Bg, long ldb, long bks, int K, char* smem, f32x4 (&acc)[MF][NF]) {
;     ...
;   for (int t = 0; t < nt - 2; t += 3) {
;     GK_STEP(t, 0, 2, false, false)
;     GK_STEP(t + 1, 1, 0, false, false)
;     GK_STEP(t + 2, 2, 1, false, false)
;   }
;   GK_STEP(nt - 2, 0, 2, false, true)
;   GK_STEP(nt - 1, 1, 0, true, true)
;     ...
;   __builtin_amdgcn_s_barrier();
;     ...
; }
; template <int MF>
; __device__ __forceinline__ void gemm_in_tile(const Params& p, int l, char* smem, int mt, int nt) {
;     ...
;   if (nt < 128) {
;     u16* dbase; long dld; int cb;
;     if (nt >= 40 && nt < 64) { dbase = p.obuf; dld = 3072; cb = (nt - 40) * 128; }
;     else { dbase = p.proj; dld = PLD; cb = nt * 128; }
; #pragma unroll
;     for (int m = 0; m < MF; ++m) {
;       int row = mt * (MF * 32) + wr * (MF * 16) + m * 16 + fr;
; #pragma unroll
;       for (int n = 0; n < 4; ++n) {
;         int col = cb + wc * 64 + n * 16 + fq * 4;
;         if (nt >= 16 && nt < 32) {
	v_mfma_f32_16x16x32_bf16 v[62:65], v[100:103], v[84:87], v[62:65]
	v_mfma_f32_16x16x32_bf16 v[58:61], v[104:107], v[84:87], v[58:61]
	v_mfma_f32_16x16x32_bf16 v[54:57], v[108:111], v[84:87], v[54:57]
	v_mfma_f32_16x16x32_bf16 v[50:53], v[112:115], v[84:87], v[50:53]
	v_lshl_add_u64 v[84:85], v[70:71], 0, s[96:97]
	global_load_lds_dwordx4 v[84:85], off
	v_lshl_add_u64 v[70:71], v[70:71], 0, s[18:19]
	s_mov_b32 m0, s39
	v_readfirstlane_b32 s39, v82
	global_load_lds_dwordx4 v[70:71], off
	v_lshl_add_u64 v[70:71], v[72:73], 0, s[2:3]
	s_mov_b32 m0, s39
	v_readfirstlane_b32 s39, v83
	global_load_lds_dwordx4 v[70:71], off
	v_lshl_add_u64 v[70:71], v[72:73], 0, s[8:9]
	s_mov_b32 m0, s39
	v_mfma_f32_16x16x32_bf16 v[46:49], v[100:103], v[88:91], v[46:49]
	global_load_lds_dwordx4 v[70:71], off
	ds_read_b128 v[70:73], v76 offset:0x8000
	v_mfma_f32_16x16x32_bf16 v[42:45], v[104:107], v[88:91], v[42:45]
	ds_read_b128 v[84:87], v76 offset:0x8400
	v_mfma_f32_16x16x32_bf16 v[38:41], v[108:111], v[88:91], v[38:41]
	v_mfma_f32_16x16x32_bf16 v[34:37], v[112:115], v[88:91], v[34:37]
	ds_read_b128 v[88:91], v76 offset:0x8800
	v_mfma_f32_16x16x32_bf16 v[30:33], v[100:103], v[92:95], v[30:33]
	v_mfma_f32_16x16x32_bf16 v[26:29], v[104:107], v[92:95], v[26:29]
	v_mfma_f32_16x16x32_bf16 v[22:25], v[108:111], v[92:95], v[22:25]
	v_mfma_f32_16x16x32_bf16 v[18:21], v[112:115], v[92:95], v[18:21]
	ds_read_b128 v[92:95], v76 offset:0x8c00
	v_mfma_f32_16x16x32_bf16 v[14:17], v[100:103], v[96:99], v[14:17]
	v_mfma_f32_16x16x32_bf16 v[10:13], v[104:107], v[96:99], v[10:13]
	v_mfma_f32_16x16x32_bf16 v[6:9], v[108:111], v[96:99], v[6:9]
	v_mfma_f32_16x16x32_bf16 v[2:5], v[112:115], v[96:99], v[2:5]
	ds_read_b128 v[96:99], v77 offset:0x8000
	ds_read_b128 v[100:103], v77 offset:0x8400
	ds_read_b128 v[104:107], v77 offset:0x8800
	ds_read_b128 v[108:111], v77 offset:0x8c00
	s_nop 0
	s_waitcnt lgkmcnt(0)
	s_nop 0
	v_mfma_f32_16x16x32_bf16 v[62:65], v[96:99], v[70:73], v[62:65]
	v_mfma_f32_16x16x32_bf16 v[58:61], v[100:103], v[70:73], v[58:61]
	v_mfma_f32_16x16x32_bf16 v[54:57], v[104:107], v[70:73], v[54:57]
	v_mfma_f32_16x16x32_bf16 v[50:53], v[108:111], v[70:73], v[50:53]
	v_mfma_f32_16x16x32_bf16 v[46:49], v[96:99], v[84:87], v[46:49]
	v_mfma_f32_16x16x32_bf16 v[42:45], v[100:103], v[84:87], v[42:45]
	v_mfma_f32_16x16x32_bf16 v[38:41], v[104:107], v[84:87], v[38:41]
	v_mfma_f32_16x16x32_bf16 v[34:37], v[108:111], v[84:87], v[34:37]
	v_mfma_f32_16x16x32_bf16 v[30:33], v[96:99], v[88:91], v[30:33]
	v_mfma_f32_16x16x32_bf16 v[26:29], v[100:103], v[88:91], v[26:29]
	v_mfma_f32_16x16x32_bf16 v[22:25], v[104:107], v[88:91], v[22:25]
	v_mfma_f32_16x16x32_bf16 v[18:21], v[108:111], v[88:91], v[18:21]
	v_mfma_f32_16x16x32_bf16 v[14:17], v[96:99], v[92:95], v[14:17]
	v_mfma_f32_16x16x32_bf16 v[10:13], v[100:103], v[92:95], v[10:13]
	v_mfma_f32_16x16x32_bf16 v[6:9], v[104:107], v[92:95], v[6:9]
	v_mfma_f32_16x16x32_bf16 v[2:5], v[108:111], v[92:95], v[2:5]
	s_cbranch_scc1 .LBB0_725
	s_waitcnt vmcnt(4)
	s_barrier
	ds_read_b128 v[66:69], v76 offset:0
	ds_read_b128 v[70:73], v76 offset:0x400
	ds_read_b128 v[78:81], v76 offset:0x800
	ds_read_b128 v[82:85], v76 offset:0xc00
	ds_read_b128 v[86:89], v77 offset:0
	ds_read_b128 v[90:93], v77 offset:0x400
	ds_read_b128 v[94:97], v77 offset:0x800
	ds_read_b128 v[98:101], v77 offset:0xc00
	s_lshl_b32 s43, s42, 7
	s_waitcnt lgkmcnt(0)
	s_sub_i32 s38, s42, 40
	v_mfma_f32_16x16x32_bf16 v[62:65], v[86:89], v[66:69], v[62:65]
	s_add_i32 s44, s43, 0xffffec00
	s_cmp_lt_u32 s38, 24
	s_waitcnt vmcnt(0)
	s_bitset1_b32 s101, 1
	v_mfma_f32_16x16x32_bf16 v[58:61], v[90:93], v[66:69], v[58:61]
	s_barrier
	s_cselect_b64 s[40:41], -1, 0
	s_and_b64 s[38:39], s[40:41], exec
	v_mfma_f32_16x16x32_bf16 v[54:57], v[94:97], v[66:69], v[54:57]
	s_cselect_b32 s43, s44, s43
	s_and_b32 s38, s42, 0x7fffff0
	s_cmp_lg_u32 s38, 16
	v_mfma_f32_16x16x32_bf16 v[50:53], v[98:101], v[66:69], v[50:53]
	ds_read_b128 v[66:69], v76 offset:0x4000
	s_cselect_b64 s[44:45], -1, 0
	s_cmp_eq_u32 s38, 16
	v_mfma_f32_16x16x32_bf16 v[46:49], v[86:89], v[70:73], v[46:49]
	s_mov_b64 s[38:39], -1
	v_mfma_f32_16x16x32_bf16 v[42:45], v[90:93], v[70:73], v[42:45]
	v_mfma_f32_16x16x32_bf16 v[38:41], v[94:97], v[70:73], v[38:41]
	v_mfma_f32_16x16x32_bf16 v[34:37], v[98:101], v[70:73], v[34:37]
	ds_read_b128 v[70:73], v76 offset:0x4400
	v_mfma_f32_16x16x32_bf16 v[30:33], v[86:89], v[78:81], v[30:33]
	v_mfma_f32_16x16x32_bf16 v[26:29], v[90:93], v[78:81], v[26:29]
	v_mfma_f32_16x16x32_bf16 v[22:25], v[94:97], v[78:81], v[22:25]
	v_mfma_f32_16x16x32_bf16 v[18:21], v[98:101], v[78:81], v[18:21]
	ds_read_b128 v[78:81], v76 offset:0x4800
	v_mfma_f32_16x16x32_bf16 v[14:17], v[86:89], v[82:85], v[14:17]
	v_mfma_f32_16x16x32_bf16 v[10:13], v[90:93], v[82:85], v[10:13]
	v_mfma_f32_16x16x32_bf16 v[6:9], v[94:97], v[82:85], v[6:9]
	v_mfma_f32_16x16x32_bf16 v[2:5], v[98:101], v[82:85], v[2:5]
	ds_read_b128 v[82:85], v76 offset:0x4c00
	ds_read_b128 v[86:89], v77 offset:0x4000
	ds_read_b128 v[90:93], v77 offset:0x4400
	ds_read_b128 v[94:97], v77 offset:0x4800
	ds_read_b128 v[74:77], v77 offset:0x4c00
	s_nop 0
	s_waitcnt lgkmcnt(0)
	s_barrier
	v_mfma_f32_16x16x32_bf16 v[62:65], v[86:89], v[66:69], v[62:65]
	v_mfma_f32_16x16x32_bf16 v[58:61], v[90:93], v[66:69], v[58:61]
	v_mfma_f32_16x16x32_bf16 v[54:57], v[94:97], v[66:69], v[54:57]
	v_mfma_f32_16x16x32_bf16 v[50:53], v[74:77], v[66:69], v[50:53]
	v_mfma_f32_16x16x32_bf16 v[46:49], v[86:89], v[70:73], v[46:49]
	v_mfma_f32_16x16x32_bf16 v[42:45], v[90:93], v[70:73], v[42:45]
	v_mfma_f32_16x16x32_bf16 v[38:41], v[94:97], v[70:73], v[38:41]
	v_mfma_f32_16x16x32_bf16 v[34:37], v[74:77], v[70:73], v[34:37]
	v_mov_b32_e32 v71, v156
	v_mfma_f32_16x16x32_bf16 v[30:33], v[86:89], v[78:81], v[30:33]
	v_mfma_f32_16x16x32_bf16 v[26:29], v[90:93], v[78:81], v[26:29]
	v_mfma_f32_16x16x32_bf16 v[22:25], v[94:97], v[78:81], v[22:25]
	v_mfma_f32_16x16x32_bf16 v[18:21], v[74:77], v[78:81], v[18:21]
	v_mfma_f32_16x16x32_bf16 v[14:17], v[86:89], v[82:85], v[14:17]
	v_mfma_f32_16x16x32_bf16 v[10:13], v[90:93], v[82:85], v[10:13]
	v_mfma_f32_16x16x32_bf16 v[6:9], v[94:97], v[82:85], v[6:9]
	v_mfma_f32_16x16x32_bf16 v[2:5], v[74:77], v[82:85], v[2:5]
	s_cbranch_scc1 .LBB0_728
	s_mov_b64 s[38:39], 0

; template <int MF, int NF>
; __device__ __forceinline__ void gemm_kloopT(const u16* Ag, long lda, long aks, const u16* Bg, long ldb, long bks, int K, char* smem, f32x4 (&acc)[MF][NF]) {
;     ...
;   GK_ISSUE(0, 0)
;   GK_ISSUE(1, 1)
;   const int co = (fq ^ (((fr >> 3) & 1) << 1)) * 16;
;     ...
;   const unsigned lds0 = (unsigned)(unsigned long)(__attribute__((address_space(3))) const char*)smem;
;   const unsigned aA = lds0 + (wr * MF * 16 + fr) * 64 + co;
;   const unsigned aB = lds0 + ASZ + (wc * NF * 16 + fr) * 64 + co;
;   for (int t = 0; t < nt - 2; t += 3) {
;     GK_STEP(t, 0, 2, false, false)
;     GK_STEP(t + 1, 1, 0, false, false)
;     GK_STEP(t + 2, 2, 1, false, false)
;   }
;   GK_STEP(nt - 2, 0, 2, false, true)
;   GK_STEP(nt - 1, 1, 0, true, true)
.LBB0_769:
	v_add_u32_e32 v187, 0xc000, v142
	v_lshl_add_u64 v[136:137], v[130:131], 0, v[0:1]
	v_readfirstlane_b32 s39, v187
	v_add_u32_e32 v187, 0xd000, v142
	v_lshl_add_u64 v[138:139], v[136:137], 0, s[16:17]
	s_mov_b32 m0, s39
	v_readfirstlane_b32 s39, v187
	v_add_u32_e32 v187, 0xe000, v142
	s_waitcnt vmcnt(6)
	s_barrier
	global_load_lds_dwordx4 v[138:139], off
	v_lshl_add_u64 v[138:139], v[136:137], 0, s[12:13]
	s_mov_b32 m0, s39
	v_readfirstlane_b32 s39, v187
	v_add_u32_e32 v187, 0xf000, v142
	global_load_lds_dwordx4 v[138:139], off
	v_lshl_add_u64 v[138:139], v[136:137], 0, s[40:41]
	s_mov_b32 m0, s39
	v_readfirstlane_b32 s39, v187
	global_load_lds_dwordx4 v[138:139], off
	v_lshl_add_u64 v[138:139], v[136:137], 0, s[44:45]
	s_mov_b32 m0, s39
	v_add_u32_e32 v187, 0x10000, v142
	global_load_lds_dwordx4 v[138:139], off
	v_lshl_add_u64 v[138:139], v[132:133], 0, v[0:1]
	v_readfirstlane_b32 s39, v187
	v_add_u32_e32 v187, 0x11000, v142
	v_lshl_add_u64 v[188:189], v[138:139], 0, s[28:29]
	s_mov_b32 m0, s39
	v_readfirstlane_b32 s39, v187
	global_load_lds_dwordx4 v[188:189], off
	v_lshl_add_u64 v[188:189], v[138:139], 0, s[30:31]
	s_mov_b32 m0, s39
	v_readfirstlane_b32 s39, v142
	global_load_lds_dwordx4 v[188:189], off
	ds_read_b128 v[188:191], v141 offset:0
	ds_read_b128 v[192:195], v141 offset:0x400
	ds_read_b128 v[200:203], v141 offset:0x800
	ds_read_b128 v[204:207], v141 offset:0xc00
	ds_read_b128 v[208:211], v141 offset:0x1000
	ds_read_b128 v[212:215], v141 offset:0x1400
	ds_read_b128 v[216:219], v141 offset:0x1800
	ds_read_b128 v[220:223], v141 offset:0x1c00
	ds_read_b128 v[224:227], v140 offset:0
	ds_read_b128 v[228:231], v140 offset:0x400
	ds_read_b128 v[232:235], v140 offset:0x800
	ds_read_b128 v[236:239], v140 offset:0xc00
	s_mov_b32 m0, s39
	s_waitcnt lgkmcnt(0)
	v_readfirstlane_b32 s39, v143
	v_mfma_f32_16x16x32_bf16 v[126:129], v[224:227], v[188:191], v[126:129]
	s_waitcnt vmcnt(6)
	s_barrier
	s_add_i32 s38, s38, 3
	v_mfma_f32_16x16x32_bf16 v[122:125], v[228:231], v[188:191], v[122:125]
	v_lshl_add_u64 v[132:133], v[132:133], 0, s[6:7]
	v_lshl_add_u64 v[130:131], v[130:131], 0, s[34:35]
	s_cmp_lt_u32 s38, 27
	v_mfma_f32_16x16x32_bf16 v[118:121], v[232:235], v[188:191], v[118:121]
	v_mfma_f32_16x16x32_bf16 v[114:117], v[236:239], v[188:191], v[114:117]
	v_lshl_add_u64 v[188:189], v[136:137], 0, s[34:35]
	global_load_lds_dwordx4 v[188:189], off
	v_lshl_add_u64 v[188:189], v[136:137], 0, s[36:37]
	s_mov_b32 m0, s39
	v_readfirstlane_b32 s39, v144
	global_load_lds_dwordx4 v[188:189], off
	v_lshl_add_u64 v[188:189], v[136:137], 0, s[48:49]
	s_mov_b32 m0, s39
	v_readfirstlane_b32 s39, v145
	global_load_lds_dwordx4 v[188:189], off
	v_lshl_add_u64 v[188:189], v[136:137], 0, s[52:53]
	s_mov_b32 m0, s39
	v_readfirstlane_b32 s39, v146
	global_load_lds_dwordx4 v[188:189], off
	v_lshl_add_u64 v[188:189], v[138:139], 0, s[6:7]
	s_mov_b32 m0, s39
	v_readfirstlane_b32 s39, v147
	global_load_lds_dwordx4 v[188:189], off
	v_lshl_add_u64 v[188:189], v[138:139], 0, s[0:1]
	s_mov_b32 m0, s39
	v_mfma_f32_16x16x32_bf16 v[110:113], v[224:227], v[192:195], v[110:113]
	global_load_lds_dwordx4 v[188:189], off
	ds_read_b128 v[188:191], v141 offset:0x6000
	v_mfma_f32_16x16x32_bf16 v[106:109], v[228:231], v[192:195], v[106:109]
	v_readfirstlane_b32 s39, v150
	s_mov_b32 m0, s39
	v_readfirstlane_b32 s39, v151
	v_mfma_f32_16x16x32_bf16 v[102:105], v[232:235], v[192:195], v[102:105]
	v_mfma_f32_16x16x32_bf16 v[98:101], v[236:239], v[192:195], v[98:101]
	ds_read_b128 v[192:195], v141 offset:0x6400
	v_mfma_f32_16x16x32_bf16 v[94:97], v[224:227], v[200:203], v[94:97]
	v_mfma_f32_16x16x32_bf16 v[90:93], v[228:231], v[200:203], v[90:93]
	v_mfma_f32_16x16x32_bf16 v[86:89], v[232:235], v[200:203], v[86:89]
	v_mfma_f32_16x16x32_bf16 v[82:85], v[236:239], v[200:203], v[82:85]
	ds_read_b128 v[200:203], v141 offset:0x6800
	v_mfma_f32_16x16x32_bf16 v[78:81], v[224:227], v[204:207], v[78:81]
	v_mfma_f32_16x16x32_bf16 v[74:77], v[228:231], v[204:207], v[74:77]
	v_mfma_f32_16x16x32_bf16 v[70:73], v[232:235], v[204:207], v[70:73]
	v_mfma_f32_16x16x32_bf16 v[66:69], v[236:239], v[204:207], v[66:69]
	ds_read_b128 v[204:207], v141 offset:0x6c00
	v_mfma_f32_16x16x32_bf16 v[62:65], v[224:227], v[208:211], v[62:65]
	v_mfma_f32_16x16x32_bf16 v[58:61], v[228:231], v[208:211], v[58:61]
	v_mfma_f32_16x16x32_bf16 v[54:57], v[232:235], v[208:211], v[54:57]
	v_mfma_f32_16x16x32_bf16 v[50:53], v[236:239], v[208:211], v[50:53]
	ds_read_b128 v[208:211], v141 offset:0x7000
	v_mfma_f32_16x16x32_bf16 v[46:49], v[224:227], v[212:215], v[46:49]
	v_mfma_f32_16x16x32_bf16 v[42:45], v[228:231], v[212:215], v[42:45]
	v_mfma_f32_16x16x32_bf16 v[38:41], v[232:235], v[212:215], v[38:41]
	v_mfma_f32_16x16x32_bf16 v[34:37], v[236:239], v[212:215], v[34:37]
	ds_read_b128 v[212:215], v141 offset:0x7400
	v_mfma_f32_16x16x32_bf16 v[30:33], v[224:227], v[216:219], v[30:33]
	v_mfma_f32_16x16x32_bf16 v[26:29], v[228:231], v[216:219], v[26:29]
	v_mfma_f32_16x16x32_bf16 v[22:25], v[232:235], v[216:219], v[22:25]
	v_mfma_f32_16x16x32_bf16 v[18:21], v[236:239], v[216:219], v[18:21]
	ds_read_b128 v[216:219], v141 offset:0x7800
	v_mfma_f32_16x16x32_bf16 v[14:17], v[224:227], v[220:223], v[14:17]
	v_mfma_f32_16x16x32_bf16 v[10:13], v[228:231], v[220:223], v[10:13]
	v_mfma_f32_16x16x32_bf16 v[6:9], v[232:235], v[220:223], v[6:9]
	v_mfma_f32_16x16x32_bf16 v[2:5], v[236:239], v[220:223], v[2:5]
	ds_read_b128 v[220:223], v141 offset:0x7c00
	ds_read_b128 v[224:227], v140 offset:0x6000
	ds_read_b128 v[228:231], v140 offset:0x6400
	ds_read_b128 v[232:235], v140 offset:0x6800
	ds_read_b128 v[236:239], v140 offset:0x6c00
	s_nop 0
	s_waitcnt lgkmcnt(0)
	s_waitcnt vmcnt(6)
	s_barrier
; template <int MF, int NF>
; __device__ __forceinline__ void gemm_kloopT(const u16* Ag, long lda, long aks, const u16* Bg, long ldb, long bks, int K, char* smem, f32x4 (&acc)[MF][NF]) {
;     ...
;   GK_ISSUE(0, 0)
;   GK_ISSUE(1, 1)
;   const int co = (fq ^ (((fr >> 3) & 1) << 1)) * 16;
;     ...
;   const unsigned lds0 = (unsigned)(unsigned long)(__attribute__((address_space(3))) const char*)smem;
;   const unsigned aA = lds0 + (wr * MF * 16 + fr) * 64 + co;
;   const unsigned aB = lds0 + ASZ + (wc * NF * 16 + fr) * 64 + co;
;   for (int t = 0; t < nt - 2; t += 3) {
;     GK_STEP(t, 0, 2, false, false)
;     GK_STEP(t + 1, 1, 0, false, false)
;     GK_STEP(t + 2, 2, 1, false, false)
;   }
;   GK_STEP(nt - 2, 0, 2, false, true)
;   GK_STEP(nt - 1, 1, 0, true, true)
	v_mfma_f32_16x16x32_bf16 v[126:129], v[224:227], v[188:191], v[126:129]
	v_mfma_f32_16x16x32_bf16 v[122:125], v[228:231], v[188:191], v[122:125]
	v_mfma_f32_16x16x32_bf16 v[118:121], v[232:235], v[188:191], v[118:121]
	v_mfma_f32_16x16x32_bf16 v[114:117], v[236:239], v[188:191], v[114:117]
	v_lshl_add_u64 v[188:189], v[136:137], 0, s[96:97]
	global_load_lds_dwordx4 v[188:189], off
	v_lshl_add_u64 v[188:189], v[136:137], 0, s[18:19]
	s_mov_b32 m0, s39
	v_readfirstlane_b32 s39, v152
	global_load_lds_dwordx4 v[188:189], off
	v_lshl_add_u64 v[188:189], v[136:137], 0, s[54:55]
	s_mov_b32 m0, s39
	v_readfirstlane_b32 s39, v153
	global_load_lds_dwordx4 v[188:189], off
	v_lshl_add_u64 v[136:137], v[136:137], 0, s[56:57]
	s_mov_b32 m0, s39
	v_readfirstlane_b32 s39, v154
	global_load_lds_dwordx4 v[136:137], off
	v_lshl_add_u64 v[136:137], v[138:139], 0, s[2:3]
	s_mov_b32 m0, s39
	v_readfirstlane_b32 s39, v155
	global_load_lds_dwordx4 v[136:137], off
	v_lshl_add_u64 v[136:137], v[138:139], 0, s[8:9]
	s_mov_b32 m0, s39
	v_mfma_f32_16x16x32_bf16 v[110:113], v[224:227], v[192:195], v[110:113]
	global_load_lds_dwordx4 v[136:137], off
	ds_read_b128 v[136:139], v141 offset:0xc000
	v_mfma_f32_16x16x32_bf16 v[106:109], v[228:231], v[192:195], v[106:109]
	ds_read_b128 v[188:191], v141 offset:0xc400
	v_mfma_f32_16x16x32_bf16 v[102:105], v[232:235], v[192:195], v[102:105]
	v_mfma_f32_16x16x32_bf16 v[98:101], v[236:239], v[192:195], v[98:101]
	ds_read_b128 v[192:195], v141 offset:0xc800
	v_mfma_f32_16x16x32_bf16 v[94:97], v[224:227], v[200:203], v[94:97]
	v_mfma_f32_16x16x32_bf16 v[90:93], v[228:231], v[200:203], v[90:93]
	v_mfma_f32_16x16x32_bf16 v[86:89], v[232:235], v[200:203], v[86:89]
	v_mfma_f32_16x16x32_bf16 v[82:85], v[236:239], v[200:203], v[82:85]
	ds_read_b128 v[200:203], v141 offset:0xcc00
	v_mfma_f32_16x16x32_bf16 v[78:81], v[224:227], v[204:207], v[78:81]
	v_mfma_f32_16x16x32_bf16 v[74:77], v[228:231], v[204:207], v[74:77]
	v_mfma_f32_16x16x32_bf16 v[70:73], v[232:235], v[204:207], v[70:73]
	v_mfma_f32_16x16x32_bf16 v[66:69], v[236:239], v[204:207], v[66:69]
	ds_read_b128 v[204:207], v141 offset:0xd000
	v_mfma_f32_16x16x32_bf16 v[62:65], v[224:227], v[208:211], v[62:65]
	v_mfma_f32_16x16x32_bf16 v[58:61], v[228:231], v[208:211], v[58:61]
	v_mfma_f32_16x16x32_bf16 v[54:57], v[232:235], v[208:211], v[54:57]
	v_mfma_f32_16x16x32_bf16 v[50:53], v[236:239], v[208:211], v[50:53]
	ds_read_b128 v[208:211], v141 offset:0xd400
	v_mfma_f32_16x16x32_bf16 v[46:49], v[224:227], v[212:215], v[46:49]
	v_mfma_f32_16x16x32_bf16 v[42:45], v[228:231], v[212:215], v[42:45]
	v_mfma_f32_16x16x32_bf16 v[38:41], v[232:235], v[212:215], v[38:41]
	v_mfma_f32_16x16x32_bf16 v[34:37], v[236:239], v[212:215], v[34:37]
	ds_read_b128 v[212:215], v141 offset:0xd800
	v_mfma_f32_16x16x32_bf16 v[30:33], v[224:227], v[216:219], v[30:33]
	v_mfma_f32_16x16x32_bf16 v[26:29], v[228:231], v[216:219], v[26:29]
	v_mfma_f32_16x16x32_bf16 v[22:25], v[232:235], v[216:219], v[22:25]
	v_mfma_f32_16x16x32_bf16 v[18:21], v[236:239], v[216:219], v[18:21]
	ds_read_b128 v[216:219], v141 offset:0xdc00
	v_mfma_f32_16x16x32_bf16 v[14:17], v[224:227], v[220:223], v[14:17]
	v_mfma_f32_16x16x32_bf16 v[10:13], v[228:231], v[220:223], v[10:13]
	v_mfma_f32_16x16x32_bf16 v[6:9], v[232:235], v[220:223], v[6:9]
	v_mfma_f32_16x16x32_bf16 v[2:5], v[236:239], v[220:223], v[2:5]
	ds_read_b128 v[220:223], v140 offset:0xc000
	ds_read_b128 v[224:227], v140 offset:0xc400
	ds_read_b128 v[228:231], v140 offset:0xc800
	ds_read_b128 v[232:235], v140 offset:0xcc00
	s_nop 0
	s_waitcnt lgkmcnt(0)
	s_nop 0
	v_mfma_f32_16x16x32_bf16 v[126:129], v[220:223], v[136:139], v[126:129]
	v_mfma_f32_16x16x32_bf16 v[122:125], v[224:227], v[136:139], v[122:125]
	v_mfma_f32_16x16x32_bf16 v[118:121], v[228:231], v[136:139], v[118:121]
	v_mfma_f32_16x16x32_bf16 v[114:117], v[232:235], v[136:139], v[114:117]
	v_mfma_f32_16x16x32_bf16 v[110:113], v[220:223], v[188:191], v[110:113]
	v_mfma_f32_16x16x32_bf16 v[106:109], v[224:227], v[188:191], v[106:109]
	v_mfma_f32_16x16x32_bf16 v[102:105], v[228:231], v[188:191], v[102:105]
	v_mfma_f32_16x16x32_bf16 v[98:101], v[232:235], v[188:191], v[98:101]
	v_mfma_f32_16x16x32_bf16 v[94:97], v[220:223], v[192:195], v[94:97]
	v_mfma_f32_16x16x32_bf16 v[90:93], v[224:227], v[192:195], v[90:93]
	v_mfma_f32_16x16x32_bf16 v[86:89], v[228:231], v[192:195], v[86:89]
	v_mfma_f32_16x16x32_bf16 v[82:85], v[232:235], v[192:195], v[82:85]
	v_mfma_f32_16x16x32_bf16 v[78:81], v[220:223], v[200:203], v[78:81]
	v_mfma_f32_16x16x32_bf16 v[74:77], v[224:227], v[200:203], v[74:77]
	v_mfma_f32_16x16x32_bf16 v[70:73], v[228:231], v[200:203], v[70:73]
	v_mfma_f32_16x16x32_bf16 v[66:69], v[232:235], v[200:203], v[66:69]
	v_mfma_f32_16x16x32_bf16 v[62:65], v[220:223], v[204:207], v[62:65]
	v_mfma_f32_16x16x32_bf16 v[58:61], v[224:227], v[204:207], v[58:61]
	v_mfma_f32_16x16x32_bf16 v[54:57], v[228:231], v[204:207], v[54:57]
	v_mfma_f32_16x16x32_bf16 v[50:53], v[232:235], v[204:207], v[50:53]
	v_mfma_f32_16x16x32_bf16 v[46:49], v[220:223], v[208:211], v[46:49]
	v_mfma_f32_16x16x32_bf16 v[42:45], v[224:227], v[208:211], v[42:45]
	v_mfma_f32_16x16x32_bf16 v[38:41], v[228:231], v[208:211], v[38:41]
	v_mfma_f32_16x16x32_bf16 v[34:37], v[232:235], v[208:211], v[34:37]
	v_mfma_f32_16x16x32_bf16 v[30:33], v[220:223], v[212:215], v[30:33]
	v_mfma_f32_16x16x32_bf16 v[26:29], v[224:227], v[212:215], v[26:29]
	v_mfma_f32_16x16x32_bf16 v[22:25], v[228:231], v[212:215], v[22:25]
	v_mfma_f32_16x16x32_bf16 v[18:21], v[232:235], v[212:215], v[18:21]
	v_mfma_f32_16x16x32_bf16 v[14:17], v[220:223], v[216:219], v[14:17]
	v_mfma_f32_16x16x32_bf16 v[10:13], v[224:227], v[216:219], v[10:13]
	v_mfma_f32_16x16x32_bf16 v[6:9], v[228:231], v[216:219], v[6:9]
	v_mfma_f32_16x16x32_bf16 v[2:5], v[232:235], v[216:219], v[2:5]
	s_cbranch_scc1 .LBB0_769
; template <int MF, int NF>
; __device__ __forceinline__ void gemm_kloopT(const u16* Ag, long lda, long aks, const u16* Bg, long ldb, long bks, int K, char* smem, f32x4 (&acc)[MF][NF]) {
;     ...
;   GK_STEP(nt - 2, 0, 2, false, true)
;   GK_STEP(nt - 1, 1, 0, true, true)
;     ...
;   __builtin_amdgcn_s_barrier();
;     ...
; }
; template <int MF>
; __device__ __forceinline__ void gemm_in_tile(const Params& p, int l, char* smem, int mt, int nt) {
;     ...
;   const int wr = (tid >> 7) & 1, wc = (tid >> 6) & 1, fr = tid & 15, fq = (tid >> 4) & 3;
;   if (nt < 128) {
	s_waitcnt vmcnt(6)
	s_barrier
	ds_read_b128 v[130:133], v141 offset:0
	ds_read_b128 v[136:139], v141 offset:0x400
	ds_read_b128 v[142:145], v141 offset:0x800
	ds_read_b128 v[150:153], v141 offset:0xc00
	ds_read_b128 v[188:191], v141 offset:0x1000
	ds_read_b128 v[192:195], v141 offset:0x1400
	ds_read_b128 v[200:203], v141 offset:0x1800
	ds_read_b128 v[204:207], v141 offset:0x1c00
	ds_read_b128 v[208:211], v140 offset:0
	ds_read_b128 v[212:215], v140 offset:0x400
	ds_read_b128 v[216:219], v140 offset:0x800
	ds_read_b128 v[220:223], v140 offset:0xc00
	v_mov_b32_e32 v0, v156
	s_waitcnt lgkmcnt(0)
	s_waitcnt vmcnt(0)
	s_bitset1_b32 s101, 1
	s_barrier
	v_mfma_f32_16x16x32_bf16 v[126:129], v[208:211], v[130:133], v[126:129]
	s_mov_b64 s[38:39], -1
	s_cmpk_gt_i32 s42, 0x7f
	v_mfma_f32_16x16x32_bf16 v[122:125], v[212:215], v[130:133], v[122:125]
	v_mfma_f32_16x16x32_bf16 v[118:121], v[216:219], v[130:133], v[118:121]
	v_mfma_f32_16x16x32_bf16 v[114:117], v[220:223], v[130:133], v[114:117]
	ds_read_b128 v[130:133], v141 offset:0x6000
	v_mfma_f32_16x16x32_bf16 v[110:113], v[208:211], v[136:139], v[110:113]
	v_mfma_f32_16x16x32_bf16 v[106:109], v[212:215], v[136:139], v[106:109]
	v_mfma_f32_16x16x32_bf16 v[102:105], v[216:219], v[136:139], v[102:105]
	v_mfma_f32_16x16x32_bf16 v[98:101], v[220:223], v[136:139], v[98:101]
	ds_read_b128 v[136:139], v141 offset:0x6400
	v_mfma_f32_16x16x32_bf16 v[94:97], v[208:211], v[142:145], v[94:97]
	v_mfma_f32_16x16x32_bf16 v[90:93], v[212:215], v[142:145], v[90:93]
	v_mfma_f32_16x16x32_bf16 v[86:89], v[216:219], v[142:145], v[86:89]
	v_mfma_f32_16x16x32_bf16 v[82:85], v[220:223], v[142:145], v[82:85]
	ds_read_b128 v[142:145], v141 offset:0x6800
	v_mfma_f32_16x16x32_bf16 v[78:81], v[208:211], v[150:153], v[78:81]
	v_mfma_f32_16x16x32_bf16 v[74:77], v[212:215], v[150:153], v[74:77]
	v_mfma_f32_16x16x32_bf16 v[70:73], v[216:219], v[150:153], v[70:73]
	v_mfma_f32_16x16x32_bf16 v[66:69], v[220:223], v[150:153], v[66:69]
	ds_read_b128 v[150:153], v141 offset:0x6c00
	v_mfma_f32_16x16x32_bf16 v[62:65], v[208:211], v[188:191], v[62:65]
	v_mfma_f32_16x16x32_bf16 v[58:61], v[212:215], v[188:191], v[58:61]
	v_mfma_f32_16x16x32_bf16 v[54:57], v[216:219], v[188:191], v[54:57]
	v_mfma_f32_16x16x32_bf16 v[50:53], v[220:223], v[188:191], v[50:53]
	ds_read_b128 v[188:191], v141 offset:0x7000
	v_mfma_f32_16x16x32_bf16 v[46:49], v[208:211], v[192:195], v[46:49]
	v_mfma_f32_16x16x32_bf16 v[42:45], v[212:215], v[192:195], v[42:45]
	v_mfma_f32_16x16x32_bf16 v[38:41], v[216:219], v[192:195], v[38:41]
	v_mfma_f32_16x16x32_bf16 v[34:37], v[220:223], v[192:195], v[34:37]
	ds_read_b128 v[192:195], v141 offset:0x7400
	v_mfma_f32_16x16x32_bf16 v[30:33], v[208:211], v[200:203], v[30:33]
	v_mfma_f32_16x16x32_bf16 v[26:29], v[212:215], v[200:203], v[26:29]
	v_mfma_f32_16x16x32_bf16 v[22:25], v[216:219], v[200:203], v[22:25]
	v_mfma_f32_16x16x32_bf16 v[18:21], v[220:223], v[200:203], v[18:21]
	ds_read_b128 v[200:203], v141 offset:0x7800
	v_mfma_f32_16x16x32_bf16 v[14:17], v[208:211], v[204:207], v[14:17]
	v_mfma_f32_16x16x32_bf16 v[10:13], v[212:215], v[204:207], v[10:13]
	v_mfma_f32_16x16x32_bf16 v[6:9], v[216:219], v[204:207], v[6:9]
	v_mfma_f32_16x16x32_bf16 v[2:5], v[220:223], v[204:207], v[2:5]
	ds_read_b128 v[204:207], v141 offset:0x7c00
	ds_read_b128 v[208:211], v140 offset:0x6000
	ds_read_b128 v[212:215], v140 offset:0x6400
	ds_read_b128 v[216:219], v140 offset:0x6800
	ds_read_b128 v[220:223], v140 offset:0x6c00
	s_nop 0
	s_waitcnt lgkmcnt(0)
	s_barrier
	v_mfma_f32_16x16x32_bf16 v[126:129], v[208:211], v[130:133], v[126:129]
	v_mfma_f32_16x16x32_bf16 v[122:125], v[212:215], v[130:133], v[122:125]
	v_mfma_f32_16x16x32_bf16 v[118:121], v[216:219], v[130:133], v[118:121]
	v_mfma_f32_16x16x32_bf16 v[114:117], v[220:223], v[130:133], v[114:117]
	v_bfe_u32 v130, v0, 6, 1
	v_bfe_u32 v131, v0, 4, 2
	v_mfma_f32_16x16x32_bf16 v[110:113], v[208:211], v[136:139], v[110:113]
	v_mfma_f32_16x16x32_bf16 v[106:109], v[212:215], v[136:139], v[106:109]
	v_mfma_f32_16x16x32_bf16 v[102:105], v[216:219], v[136:139], v[102:105]
	v_mfma_f32_16x16x32_bf16 v[98:101], v[220:223], v[136:139], v[98:101]
	v_bfe_u32 v137, v0, 7, 1
	v_and_b32_e32 v138, 15, v0
	v_mfma_f32_16x16x32_bf16 v[94:97], v[208:211], v[142:145], v[94:97]
	v_mfma_f32_16x16x32_bf16 v[90:93], v[212:215], v[142:145], v[90:93]
	v_mfma_f32_16x16x32_bf16 v[86:89], v[216:219], v[142:145], v[86:89]
	v_mfma_f32_16x16x32_bf16 v[82:85], v[220:223], v[142:145], v[82:85]
	v_mfma_f32_16x16x32_bf16 v[78:81], v[208:211], v[150:153], v[78:81]
	v_mfma_f32_16x16x32_bf16 v[74:77], v[212:215], v[150:153], v[74:77]
	v_mfma_f32_16x16x32_bf16 v[70:73], v[216:219], v[150:153], v[70:73]
	v_mfma_f32_16x16x32_bf16 v[66:69], v[220:223], v[150:153], v[66:69]
	v_mfma_f32_16x16x32_bf16 v[62:65], v[208:211], v[188:191], v[62:65]
	v_mfma_f32_16x16x32_bf16 v[58:61], v[212:215], v[188:191], v[58:61]
	v_mfma_f32_16x16x32_bf16 v[54:57], v[216:219], v[188:191], v[54:57]
	v_mfma_f32_16x16x32_bf16 v[50:53], v[220:223], v[188:191], v[50:53]
	v_mfma_f32_16x16x32_bf16 v[46:49], v[208:211], v[192:195], v[46:49]
	v_mfma_f32_16x16x32_bf16 v[42:45], v[212:215], v[192:195], v[42:45]
	v_mfma_f32_16x16x32_bf16 v[38:41], v[216:219], v[192:195], v[38:41]
	v_mfma_f32_16x16x32_bf16 v[34:37], v[220:223], v[192:195], v[34:37]
	v_mfma_f32_16x16x32_bf16 v[30:33], v[208:211], v[200:203], v[30:33]
	v_mfma_f32_16x16x32_bf16 v[26:29], v[212:215], v[200:203], v[26:29]
	v_mfma_f32_16x16x32_bf16 v[22:25], v[216:219], v[200:203], v[22:25]
	v_mfma_f32_16x16x32_bf16 v[18:21], v[220:223], v[200:203], v[18:21]
	v_mfma_f32_16x16x32_bf16 v[14:17], v[208:211], v[204:207], v[14:17]
	v_mfma_f32_16x16x32_bf16 v[10:13], v[212:215], v[204:207], v[10:13]
	v_mfma_f32_16x16x32_bf16 v[6:9], v[216:219], v[204:207], v[6:9]
	v_mfma_f32_16x16x32_bf16 v[2:5], v[220:223], v[204:207], v[2:5]
	s_cbranch_scc0 .LBB0_774
; template <int MF>
; __device__ __forceinline__ void gemm_in_tile(const Params& p, int l, char* smem, int mt, int nt) {
;     ...
;   } else if (wc == 0) {
; #pragma unroll
;     for (int m = 0; m < MF; ++m) {
;       int row = mt * (MF * 32) + wr * (MF * 16) + m * 16 + fr;
; #pragma unroll
;       for (int n = 0; n < 4; ++n) {
;         int col = n * 16 + fq * 4;
;         *(float4*)(p.gates + (long)row * GLD + col) = float4{acc[m][n][0], acc[m][n][1], acc[m][n][2], acc[m][n][3]};
;       }
;     }
;   }
	v_cmp_eq_u32_e32 vcc, 0, v130
	s_and_saveexec_b64 s[38:39], vcc
	s_cbranch_execz .LBB0_773
	s_lshl_b32 s40, s46, 8
	v_lshlrev_b32_e32 v0, 7, v137
	v_or3_b32 v132, v0, s40, v138
	v_ashrrev_i32_e32 v133, 31, v132
	v_readlane_b32 s52, v240, 6
	v_lshlrev_b64 v[140:141], 8, v[132:133]
	v_readlane_b32 s53, v240, 7
	v_lshlrev_b32_e32 v0, 4, v131
	v_readlane_b32 s54, v240, 8
	v_lshl_add_u64 v[140:141], s[52:53], 0, v[140:141]
	v_lshl_add_u64 v[140:141], v[140:141], 0, v[0:1]
	global_store_dwordx4 v[140:141], v[126:129], off
	global_store_dwordx4 v[140:141], v[122:125], off offset:64
	global_store_dwordx4 v[140:141], v[118:121], off offset:128
	global_store_dwordx4 v[140:141], v[114:117], off offset:192
	v_or_b32_e32 v140, 16, v132
	v_ashrrev_i32_e32 v141, 31, v140
	v_lshlrev_b64 v[140:141], 8, v[140:141]
	v_lshl_add_u64 v[140:141], s[52:53], 0, v[140:141]
	v_lshl_add_u64 v[140:141], v[140:141], 0, v[0:1]
	global_store_dwordx4 v[140:141], v[110:113], off
	global_store_dwordx4 v[140:141], v[106:109], off offset:64
	global_store_dwordx4 v[140:141], v[102:105], off offset:128
	global_store_dwordx4 v[140:141], v[98:101], off offset:192
	v_or_b32_e32 v140, 32, v132
	v_ashrrev_i32_e32 v141, 31, v140
	v_lshlrev_b64 v[140:141], 8, v[140:141]
	v_lshl_add_u64 v[140:141], s[52:53], 0, v[140:141]
	v_lshl_add_u64 v[140:141], v[140:141], 0, v[0:1]
	global_store_dwordx4 v[140:141], v[94:97], off
	global_store_dwordx4 v[140:141], v[90:93], off offset:64
	global_store_dwordx4 v[140:141], v[86:89], off offset:128
	global_store_dwordx4 v[140:141], v[82:85], off offset:192
	v_or_b32_e32 v140, 48, v132
	v_ashrrev_i32_e32 v141, 31, v140
	v_lshlrev_b64 v[140:141], 8, v[140:141]
	v_lshl_add_u64 v[140:141], s[52:53], 0, v[140:141]
	v_lshl_add_u64 v[140:141], v[140:141], 0, v[0:1]
	global_store_dwordx4 v[140:141], v[78:81], off
	global_store_dwordx4 v[140:141], v[74:77], off offset:64
	global_store_dwordx4 v[140:141], v[70:73], off offset:128
	global_store_dwordx4 v[140:141], v[66:69], off offset:192
	v_or_b32_e32 v140, 64, v132
	v_ashrrev_i32_e32 v141, 31, v140
	v_lshlrev_b64 v[140:141], 8, v[140:141]
	v_lshl_add_u64 v[140:141], s[52:53], 0, v[140:141]
	v_lshl_add_u64 v[140:141], v[140:141], 0, v[0:1]
	global_store_dwordx4 v[140:141], v[62:65], off
	global_store_dwordx4 v[140:141], v[58:61], off offset:64
	global_store_dwordx4 v[140:141], v[54:57], off offset:128
	global_store_dwordx4 v[140:141], v[50:53], off offset:192
	v_or_b32_e32 v140, 0x50, v132
	v_ashrrev_i32_e32 v141, 31, v140
	v_lshlrev_b64 v[140:141], 8, v[140:141]
	v_lshl_add_u64 v[140:141], s[52:53], 0, v[140:141]
	v_lshl_add_u64 v[140:141], v[140:141], 0, v[0:1]
	global_store_dwordx4 v[140:141], v[46:49], off
	global_store_dwordx4 v[140:141], v[42:45], off offset:64
	global_store_dwordx4 v[140:141], v[38:41], off offset:128
	global_store_dwordx4 v[140:141], v[34:37], off offset:192
	v_or_b32_e32 v140, 0x60, v132
	v_or_b32_e32 v132, 0x70, v132
	v_ashrrev_i32_e32 v141, 31, v140
	v_ashrrev_i32_e32 v133, 31, v132
	v_lshlrev_b64 v[140:141], 8, v[140:141]
	v_lshlrev_b64 v[132:133], 8, v[132:133]
	v_lshl_add_u64 v[140:141], s[52:53], 0, v[140:141]
	v_lshl_add_u64 v[132:133], s[52:53], 0, v[132:133]
	v_lshl_add_u64 v[140:141], v[140:141], 0, v[0:1]
	v_lshl_add_u64 v[132:133], v[132:133], 0, v[0:1]
	v_readlane_b32 s55, v240, 9
	global_store_dwordx4 v[140:141], v[30:33], off
	global_store_dwordx4 v[140:141], v[26:29], off offset:64
	global_store_dwordx4 v[140:141], v[22:25], off offset:128
	global_store_dwordx4 v[140:141], v[18:21], off offset:192
	global_store_dwordx4 v[132:133], v[14:17], off
	global_store_dwordx4 v[132:133], v[10:13], off offset:64
	global_store_dwordx4 v[132:133], v[6:9], off offset:128
	global_store_dwordx4 v[132:133], v[2:5], off offset:192

; template <int MF, int NF>
; __device__ __forceinline__ void gemm_kloopT(const u16* Ag, long lda, long aks, const u16* Bg, long ldb, long bks, int K, char* smem, f32x4 (&acc)[MF][NF]) {
;     ...
;   GK_ISSUE(0, 0)
;   GK_ISSUE(1, 1)
;   const int co = (fq ^ (((fr >> 3) & 1) << 1)) * 16;
;     ...
;   const unsigned lds0 = (unsigned)(unsigned long)(__attribute__((address_space(3))) const char*)smem;
;   const unsigned aA = lds0 + (wr * MF * 16 + fr) * 64 + co;
;   const unsigned aB = lds0 + ASZ + (wc * NF * 16 + fr) * 64 + co;
;   for (int t = 0; t < nt - 2; t += 3) {
;     GK_STEP(t, 0, 2, false, false)
;     GK_STEP(t + 1, 1, 0, false, false)
;     GK_STEP(t + 2, 2, 1, false, false)
;   }
;   GK_STEP(nt - 2, 0, 2, false, true)
;   GK_STEP(nt - 1, 1, 0, true, true)
.LBB0_998:
	v_add_u32_e32 v202, 0x8000, v190
	v_lshl_add_u64 v[200:201], v[152:153], 0, v[0:1]
	v_readfirstlane_b32 s75, v202
	v_add_u32_e32 v202, 0x9000, v190
	s_mov_b32 m0, s75
	v_readfirstlane_b32 s75, v202
	v_add_u32_e32 v202, 0xa000, v190
	s_waitcnt vmcnt(4)
	s_barrier
	global_load_lds_dwordx4 v[200:201], off
	v_lshl_add_u64 v[200:201], v[154:155], 0, v[0:1]
	s_mov_b32 m0, s75
	v_readfirstlane_b32 s75, v202
	v_add_u32_e32 v202, 0xb000, v190
	global_load_lds_dwordx4 v[200:201], off
	v_lshl_add_u64 v[200:201], v[146:147], 0, v[0:1]
	s_mov_b32 m0, s75
	v_readfirstlane_b32 s75, v202
	global_load_lds_dwordx4 v[200:201], off
	v_lshl_add_u64 v[200:201], v[150:151], 0, v[0:1]
	s_mov_b32 m0, s75
	v_readfirstlane_b32 s75, v190
	global_load_lds_dwordx4 v[200:201], off
	ds_read_b128 v[200:203], v189 offset:0
	ds_read_b128 v[204:207], v189 offset:0x400
	ds_read_b128 v[208:211], v189 offset:0x800
	ds_read_b128 v[212:215], v189 offset:0xc00
	ds_read_b128 v[216:219], v188 offset:0
	ds_read_b128 v[220:223], v188 offset:0x400
	ds_read_b128 v[224:227], v188 offset:0x800
	ds_read_b128 v[228:231], v188 offset:0xc00
	s_mov_b32 m0, s75
	s_waitcnt lgkmcnt(0)
	v_readfirstlane_b32 s75, v191
	v_mfma_f32_16x16x32_bf16 v[62:65], v[216:219], v[200:203], v[62:65]
	s_waitcnt vmcnt(4)
	s_barrier
	s_add_i32 s74, s74, 3
	v_mfma_f32_16x16x32_bf16 v[58:61], v[220:223], v[200:203], v[58:61]
	v_lshl_add_u64 v[146:147], v[146:147], 0, s[22:23]
	v_lshl_add_u64 v[150:151], v[150:151], 0, s[22:23]
	v_lshl_add_u64 v[152:153], v[152:153], 0, s[94:95]
	v_mfma_f32_16x16x32_bf16 v[54:57], v[224:227], v[200:203], v[54:57]
	v_lshl_add_u64 v[154:155], v[154:155], 0, s[94:95]
	s_cmp_lt_u32 s74, 27
	v_mfma_f32_16x16x32_bf16 v[50:53], v[228:231], v[200:203], v[50:53]
	v_lshl_add_u64 v[200:201], v[142:143], 0, v[0:1]
	global_load_lds_dwordx4 v[200:201], off
	v_lshl_add_u64 v[200:201], v[144:145], 0, v[0:1]
	s_mov_b32 m0, s75
	v_readfirstlane_b32 s75, v192
	global_load_lds_dwordx4 v[200:201], off
	v_lshl_add_u64 v[200:201], v[138:139], 0, v[0:1]
	s_mov_b32 m0, s75
	v_readfirstlane_b32 s75, v193
	global_load_lds_dwordx4 v[200:201], off
	v_lshl_add_u64 v[200:201], v[140:141], 0, v[0:1]
	s_mov_b32 m0, s75
	v_mfma_f32_16x16x32_bf16 v[46:49], v[216:219], v[204:207], v[46:49]
	global_load_lds_dwordx4 v[200:201], off
	ds_read_b128 v[200:203], v189 offset:0x4000
	v_mfma_f32_16x16x32_bf16 v[42:45], v[220:223], v[204:207], v[42:45]
	v_readfirstlane_b32 s75, v194
	s_mov_b32 m0, s75
	v_readfirstlane_b32 s75, v195
	v_mfma_f32_16x16x32_bf16 v[38:41], v[224:227], v[204:207], v[38:41]
	v_lshl_add_u64 v[138:139], v[138:139], 0, s[22:23]
	v_lshl_add_u64 v[140:141], v[140:141], 0, s[22:23]
	v_lshl_add_u64 v[142:143], v[142:143], 0, s[94:95]
	v_mfma_f32_16x16x32_bf16 v[34:37], v[228:231], v[204:207], v[34:37]
	ds_read_b128 v[204:207], v189 offset:0x4400
	v_lshl_add_u64 v[144:145], v[144:145], 0, s[94:95]
	v_mfma_f32_16x16x32_bf16 v[30:33], v[216:219], v[208:211], v[30:33]
	v_mfma_f32_16x16x32_bf16 v[26:29], v[220:223], v[208:211], v[26:29]
	v_mfma_f32_16x16x32_bf16 v[22:25], v[224:227], v[208:211], v[22:25]
	v_mfma_f32_16x16x32_bf16 v[18:21], v[228:231], v[208:211], v[18:21]
	ds_read_b128 v[208:211], v189 offset:0x4800
	v_mfma_f32_16x16x32_bf16 v[14:17], v[216:219], v[212:215], v[14:17]
	v_mfma_f32_16x16x32_bf16 v[10:13], v[220:223], v[212:215], v[10:13]
	v_mfma_f32_16x16x32_bf16 v[6:9], v[224:227], v[212:215], v[6:9]
	v_mfma_f32_16x16x32_bf16 v[2:5], v[228:231], v[212:215], v[2:5]
	ds_read_b128 v[212:215], v189 offset:0x4c00
	ds_read_b128 v[216:219], v188 offset:0x4000
	ds_read_b128 v[220:223], v188 offset:0x4400
	ds_read_b128 v[224:227], v188 offset:0x4800
	ds_read_b128 v[228:231], v188 offset:0x4c00
	s_nop 0
	s_waitcnt lgkmcnt(0)
	s_waitcnt vmcnt(4)
	s_barrier
	v_mfma_f32_16x16x32_bf16 v[62:65], v[216:219], v[200:203], v[62:65]
	v_mfma_f32_16x16x32_bf16 v[58:61], v[220:223], v[200:203], v[58:61]
	v_mfma_f32_16x16x32_bf16 v[54:57], v[224:227], v[200:203], v[54:57]
	v_mfma_f32_16x16x32_bf16 v[50:53], v[228:231], v[200:203], v[50:53]
	v_lshl_add_u64 v[200:201], v[134:135], 0, v[0:1]
	global_load_lds_dwordx4 v[200:201], off
	v_lshl_add_u64 v[200:201], v[136:137], 0, v[0:1]
	s_mov_b32 m0, s75
	v_readfirstlane_b32 s75, v196
	global_load_lds_dwordx4 v[200:201], off
	v_lshl_add_u64 v[200:201], v[130:131], 0, v[0:1]
	s_mov_b32 m0, s75
	v_readfirstlane_b32 s75, v197
	global_load_lds_dwordx4 v[200:201], off
	v_lshl_add_u64 v[200:201], v[132:133], 0, v[0:1]
	s_mov_b32 m0, s75
	v_mfma_f32_16x16x32_bf16 v[46:49], v[216:219], v[204:207], v[46:49]
	global_load_lds_dwordx4 v[200:201], off
	ds_read_b128 v[200:203], v189 offset:0x8000
	v_mfma_f32_16x16x32_bf16 v[42:45], v[220:223], v[204:207], v[42:45]
	v_lshl_add_u64 v[130:131], v[130:131], 0, s[22:23]
	v_lshl_add_u64 v[132:133], v[132:133], 0, s[22:23]
	v_lshl_add_u64 v[134:135], v[134:135], 0, s[94:95]
	v_mfma_f32_16x16x32_bf16 v[38:41], v[224:227], v[204:207], v[38:41]
	v_lshl_add_u64 v[136:137], v[136:137], 0, s[94:95]
	v_mfma_f32_16x16x32_bf16 v[34:37], v[228:231], v[204:207], v[34:37]
	ds_read_b128 v[204:207], v189 offset:0x8400
	v_mfma_f32_16x16x32_bf16 v[30:33], v[216:219], v[208:211], v[30:33]
	v_mfma_f32_16x16x32_bf16 v[26:29], v[220:223], v[208:211], v[26:29]
	v_mfma_f32_16x16x32_bf16 v[22:25], v[224:227], v[208:211], v[22:25]
	v_mfma_f32_16x16x32_bf16 v[18:21], v[228:231], v[208:211], v[18:21]
	ds_read_b128 v[208:211], v189 offset:0x8800
	v_mfma_f32_16x16x32_bf16 v[14:17], v[216:219], v[212:215], v[14:17]
	v_mfma_f32_16x16x32_bf16 v[10:13], v[220:223], v[212:215], v[10:13]
	v_mfma_f32_16x16x32_bf16 v[6:9], v[224:227], v[212:215], v[6:9]
	v_mfma_f32_16x16x32_bf16 v[2:5], v[228:231], v[212:215], v[2:5]
	ds_read_b128 v[212:215], v189 offset:0x8c00
	ds_read_b128 v[216:219], v188 offset:0x8000
	ds_read_b128 v[220:223], v188 offset:0x8400
	ds_read_b128 v[224:227], v188 offset:0x8800
	ds_read_b128 v[228:231], v188 offset:0x8c00
	s_nop 0
	s_waitcnt lgkmcnt(0)
; __device__ __forceinline__ float sigmoidf_(float x) { return __builtin_amdgcn_rcpf(1.f + __expf(-x)); }
; __device__ __forceinline__ int otid() { int t = threadIdx.x; asm volatile("" : "+v"(t)); return t; }
; template <int MF, int NF>
; __device__ __forceinline__ void gemm_kloopT(const u16* Ag, long lda, long aks, const u16* Bg, long ldb, long bks, int K, char* smem, f32x4 (&acc)[MF][NF]) {
;     ...
;   GK_STEP(nt - 2, 0, 2, false, true)
;   GK_STEP(nt - 1, 1, 0, true, true)
;     ...
;   __builtin_amdgcn_s_barrier();
;     ...
; }
; __device__ void ph_gemm_merge(const Params& p, int l, char* smem) {
;     ...
;       gemm_kloopT<4, 4>(p.obuf + (long)mt * 128 * 3072 + i * 1024, 3072, 32, p.WbrT + (long)i * D * D + (long)nt * 128 * 32, 32, (long)D * 32, D, smem, acc);
;       const int tid2 = otid();
;       const int wr = (tid2 >> 7) & 1, wc = (tid2 >> 6) & 1, fr = tid2 & 15, fq = (tid2 >> 4) & 3;
; #pragma unroll
;       for (int m = 0; m < 4; ++m) {
;         int row = mt * 128 + wr * 64 + m * 16 + fr;
; #pragma unroll
;         for (int n = 0; n < 4; ++n) {
;           int col = nt * 128 + wc * 64 + n * 16 + fq * 4;
;           uint2 gr = *(const uint2*)(p.proj + (long)row * PLD + C_GATE + i * 1024 + col);
;           tot[m][n][0] += sigmoidf_(__uint_as_float(gr.x << 16)) * acc[m][n][0];
;           tot[m][n][1] += sigmoidf_(__uint_as_float(gr.x & 0xffff0000u)) * acc[m][n][1];
;           tot[m][n][2] += sigmoidf_(__uint_as_float(gr.y << 16)) * acc[m][n][2];
;           tot[m][n][3] += sigmoidf_(__uint_as_float(gr.y & 0xffff0000u)) * acc[m][n][3];
;         }
	s_nop 0
	v_mfma_f32_16x16x32_bf16 v[62:65], v[216:219], v[200:203], v[62:65]
	v_mfma_f32_16x16x32_bf16 v[58:61], v[220:223], v[200:203], v[58:61]
	v_mfma_f32_16x16x32_bf16 v[54:57], v[224:227], v[200:203], v[54:57]
	v_mfma_f32_16x16x32_bf16 v[50:53], v[228:231], v[200:203], v[50:53]
	v_mfma_f32_16x16x32_bf16 v[46:49], v[216:219], v[204:207], v[46:49]
	v_mfma_f32_16x16x32_bf16 v[42:45], v[220:223], v[204:207], v[42:45]
	v_mfma_f32_16x16x32_bf16 v[38:41], v[224:227], v[204:207], v[38:41]
	v_mfma_f32_16x16x32_bf16 v[34:37], v[228:231], v[204:207], v[34:37]
	v_mfma_f32_16x16x32_bf16 v[30:33], v[216:219], v[208:211], v[30:33]
	v_mfma_f32_16x16x32_bf16 v[26:29], v[220:223], v[208:211], v[26:29]
	v_mfma_f32_16x16x32_bf16 v[22:25], v[224:227], v[208:211], v[22:25]
	v_mfma_f32_16x16x32_bf16 v[18:21], v[228:231], v[208:211], v[18:21]
	v_mfma_f32_16x16x32_bf16 v[14:17], v[216:219], v[212:215], v[14:17]
	v_mfma_f32_16x16x32_bf16 v[10:13], v[220:223], v[212:215], v[10:13]
	v_mfma_f32_16x16x32_bf16 v[6:9], v[224:227], v[212:215], v[6:9]
	v_mfma_f32_16x16x32_bf16 v[2:5], v[228:231], v[212:215], v[2:5]
	s_cbranch_scc1 .LBB0_998
	s_waitcnt vmcnt(4)
	s_barrier
	ds_read_b128 v[130:133], v189 offset:0
	ds_read_b128 v[134:137], v189 offset:0x400
	ds_read_b128 v[138:141], v189 offset:0x800
	ds_read_b128 v[142:145], v189 offset:0xc00
	ds_read_b128 v[150:153], v188 offset:0
	ds_read_b128 v[190:193], v188 offset:0x400
	ds_read_b128 v[194:197], v188 offset:0x800
	ds_read_b128 v[200:203], v188 offset:0xc00
	v_mov_b32_e32 v0, v156
	s_waitcnt lgkmcnt(0)
	s_waitcnt vmcnt(0)
	s_barrier
	v_mfma_f32_16x16x32_bf16 v[58:61], v[190:193], v[130:133], v[58:61]
	s_lshl_b32 s92, s73, 1
	s_add_i32 s72, s72, 1
	s_add_u32 s40, s40, 0x200000
	v_mfma_f32_16x16x32_bf16 v[62:65], v[150:153], v[130:133], v[62:65]
	s_addc_u32 s41, s41, 0
	s_add_u32 s42, s42, 0x200000
	s_addc_u32 s43, s43, 0
	v_mfma_f32_16x16x32_bf16 v[54:57], v[194:197], v[130:133], v[54:57]
	s_add_u32 s44, s44, 0x800
	s_addc_u32 s45, s45, 0
	s_add_u32 s46, s46, 0x800
	v_mfma_f32_16x16x32_bf16 v[50:53], v[200:203], v[130:133], v[50:53]
	ds_read_b128 v[130:133], v189 offset:0x4000
	s_addc_u32 s47, s47, 0
	s_add_u32 s48, s48, 0x200000
	v_mfma_f32_16x16x32_bf16 v[46:49], v[150:153], v[134:137], v[46:49]
	s_addc_u32 s49, s49, 0
	s_add_u32 s50, s50, 0x200000
	s_addc_u32 s51, s51, 0
	v_mfma_f32_16x16x32_bf16 v[42:45], v[190:193], v[134:137], v[42:45]
	s_add_u32 s52, s52, 0x800
	s_addc_u32 s53, s53, 0
	s_add_u32 s54, s54, 0x800
	v_mfma_f32_16x16x32_bf16 v[38:41], v[194:197], v[134:137], v[38:41]
	s_addc_u32 s55, s55, 0
	s_add_u32 s56, s56, 0x200000
	s_addc_u32 s57, s57, 0
	v_mfma_f32_16x16x32_bf16 v[34:37], v[200:203], v[134:137], v[34:37]
	ds_read_b128 v[134:137], v189 offset:0x4400
	s_add_u32 s58, s58, 0x200000
	s_addc_u32 s59, s59, 0
	v_mfma_f32_16x16x32_bf16 v[30:33], v[150:153], v[138:141], v[30:33]
	s_add_u32 s60, s60, 0x800
	s_addc_u32 s61, s61, 0
	s_add_u32 s62, s62, 0x800
	v_mfma_f32_16x16x32_bf16 v[26:29], v[190:193], v[138:141], v[26:29]
	s_addc_u32 s63, s63, 0
	s_cmp_eq_u32 s72, 3
	v_mfma_f32_16x16x32_bf16 v[22:25], v[194:197], v[138:141], v[22:25]
	v_mfma_f32_16x16x32_bf16 v[18:21], v[200:203], v[138:141], v[18:21]
	ds_read_b128 v[138:141], v189 offset:0x4800
	v_mfma_f32_16x16x32_bf16 v[14:17], v[150:153], v[142:145], v[14:17]
	v_mfma_f32_16x16x32_bf16 v[10:13], v[190:193], v[142:145], v[10:13]
	v_mfma_f32_16x16x32_bf16 v[6:9], v[194:197], v[142:145], v[6:9]
	v_mfma_f32_16x16x32_bf16 v[2:5], v[200:203], v[142:145], v[2:5]
	ds_read_b128 v[142:145], v189 offset:0x4c00
	ds_read_b128 v[150:153], v188 offset:0x4000
	ds_read_b128 v[190:193], v188 offset:0x4400
	ds_read_b128 v[194:197], v188 offset:0x4800
	ds_read_b128 v[200:203], v188 offset:0x4c00
	s_nop 0
	s_waitcnt lgkmcnt(0)
	s_barrier
	v_mfma_f32_16x16x32_bf16 v[204:207], v[190:193], v[130:133], v[58:61]
	v_mfma_f32_16x16x32_bf16 v[62:65], v[150:153], v[130:133], v[62:65]
	s_nop 1
	v_lshrrev_b32_e32 v60, 1, v0
	v_and_b32_e32 v59, 64, v0
	v_and_b32_e32 v58, 15, v0
	v_and_b32_e32 v60, 64, v60
	v_lshrrev_b32_e32 v0, 2, v0
	v_or3_b32 v58, v58, v60, s67
	v_and_b32_e32 v0, 12, v0
	v_or3_b32 v60, v59, v0, s66
	v_ashrrev_i32_e32 v59, 31, v58
	v_mfma_f32_16x16x32_bf16 v[54:57], v[194:197], v[130:133], v[54:57]
	v_ashrrev_i32_e32 v61, 31, v60
	v_lshlrev_b64 v[60:61], 1, v[60:61]
	v_mfma_f32_16x16x32_bf16 v[50:53], v[200:203], v[130:133], v[50:53]
	v_lshlrev_b64 v[130:131], 15, v[58:59]
	v_lshl_add_u64 v[130:131], s[86:87], 0, v[130:131]
	v_lshl_add_u64 v[130:131], v[130:131], 0, s[92:93]
	v_lshl_add_u64 v[130:131], v[130:131], 0, v[60:61]
	v_lshl_add_u64 v[132:133], v[130:131], 0, s[20:21]
	v_add_co_u32_e32 v130, vcc, s4, v130
	v_mfma_f32_16x16x32_bf16 v[46:49], v[150:153], v[134:137], v[46:49]
	s_nop 0
	v_addc_co_u32_e32 v131, vcc, 0, v131, vcc
	global_load_dwordx2 v[130:131], v[130:131], off offset:2048
	global_load_dwordx2 v[232:233], v[132:133], off offset:32
	global_load_dwordx2 v[234:235], v[132:133], off offset:64
	global_load_dwordx2 v[236:237], v[132:133], off offset:96
	v_mfma_f32_16x16x32_bf16 v[42:45], v[190:193], v[134:137], v[42:45]
	s_waitcnt vmcnt(3)
; __device__ __forceinline__ float sigmoidf_(float x) { return __builtin_amdgcn_rcpf(1.f + __expf(-x)); }
; __device__ void ph_gemm_merge(const Params& p, int l, char* smem) {
;     ...
; #pragma unroll
;       for (int m = 0; m < 4; ++m) {
;         int row = mt * 128 + wr * 64 + m * 16 + fr;
; #pragma unroll
;         for (int n = 0; n < 4; ++n) {
;           int col = nt * 128 + wc * 64 + n * 16 + fq * 4;
;           uint2 gr = *(const uint2*)(p.proj + (long)row * PLD + C_GATE + i * 1024 + col);
;           tot[m][n][0] += sigmoidf_(__uint_as_float(gr.x << 16)) * acc[m][n][0];
;           tot[m][n][1] += sigmoidf_(__uint_as_float(gr.x & 0xffff0000u)) * acc[m][n][1];
;           tot[m][n][2] += sigmoidf_(__uint_as_float(gr.y << 16)) * acc[m][n][2];
;           tot[m][n][3] += sigmoidf_(__uint_as_float(gr.y & 0xffff0000u)) * acc[m][n][3];
;         }
	v_lshlrev_b32_e32 v0, 16, v130
	v_mul_f32_e32 v0, 0xbfb8aa3b, v0
	v_exp_f32_e32 v0, v0
	v_mfma_f32_16x16x32_bf16 v[38:41], v[194:197], v[134:137], v[38:41]
	v_add_f32_e32 v0, 1.0, v0
	v_mfma_f32_16x16x32_bf16 v[34:37], v[200:203], v[134:137], v[34:37]
	v_rcp_f32_e32 v134, v0
	v_and_b32_e32 v0, 0xffff0000, v130
	v_mul_f32_e32 v0, 0xbfb8aa3b, v0
	v_exp_f32_e32 v0, v0
	v_mfma_f32_16x16x32_bf16 v[30:33], v[150:153], v[138:141], v[30:33]
	v_add_f32_e32 v0, 1.0, v0
	v_rcp_f32_e32 v135, v0
	v_lshlrev_b32_e32 v0, 16, v131
	v_mul_f32_e32 v0, 0xbfb8aa3b, v0
	v_exp_f32_e32 v0, v0
	v_pk_fma_f32 v[126:127], v[62:63], v[134:135], v[126:127]
	v_mfma_f32_16x16x32_bf16 v[26:29], v[190:193], v[138:141], v[26:29]
	v_add_f32_e32 v0, 1.0, v0
	v_rcp_f32_e32 v62, v0
	v_and_b32_e32 v0, 0xffff0000, v131
	v_mul_f32_e32 v0, 0xbfb8aa3b, v0
	v_exp_f32_e32 v0, v0
	v_mfma_f32_16x16x32_bf16 v[22:25], v[194:197], v[138:141], v[22:25]
	v_add_f32_e32 v0, 1.0, v0
	v_rcp_f32_e32 v63, v0
	v_mfma_f32_16x16x32_bf16 v[18:21], v[200:203], v[138:141], v[18:21]
	v_fma_f32 v128, v64, v62, v128
	v_fma_f32 v129, v65, v63, v129
	v_mfma_f32_16x16x32_bf16 v[14:17], v[150:153], v[142:145], v[14:17]
	s_waitcnt vmcnt(2)
	v_lshlrev_b32_e32 v0, 16, v232
	v_mul_f32_e32 v0, 0xbfb8aa3b, v0
	v_exp_f32_e32 v0, v0
	v_mfma_f32_16x16x32_bf16 v[10:13], v[190:193], v[142:145], v[10:13]
	v_add_f32_e32 v0, 1.0, v0
	v_rcp_f32_e32 v64, v0
	v_and_b32_e32 v0, 0xffff0000, v232
	v_mul_f32_e32 v0, 0xbfb8aa3b, v0
	v_exp_f32_e32 v0, v0
	v_mfma_f32_16x16x32_bf16 v[6:9], v[194:197], v[142:145], v[6:9]
	v_add_f32_e32 v0, 1.0, v0
	v_rcp_f32_e32 v65, v0
	v_lshlrev_b32_e32 v0, 16, v233
	v_mul_f32_e32 v0, 0xbfb8aa3b, v0
	v_exp_f32_e32 v0, v0
	v_pk_fma_f32 v[122:123], v[204:205], v[64:65], v[122:123]
	v_mfma_f32_16x16x32_bf16 v[2:5], v[200:203], v[142:145], v[2:5]
	v_add_f32_e32 v0, 1.0, v0
	v_rcp_f32_e32 v62, v0
	v_and_b32_e32 v0, 0xffff0000, v233
	v_mul_f32_e32 v0, 0xbfb8aa3b, v0
	v_exp_f32_e32 v0, v0
	s_nop 0
	v_add_f32_e32 v0, 1.0, v0
	v_rcp_f32_e32 v63, v0
	s_nop 0
	v_pk_fma_f32 v[124:125], v[206:207], v[62:63], v[124:125]
	s_waitcnt vmcnt(1)
	v_lshlrev_b32_e32 v0, 16, v234
	v_mul_f32_e32 v0, 0xbfb8aa3b, v0
	v_exp_f32_e32 v0, v0
	s_nop 0
	v_add_f32_e32 v0, 1.0, v0
	v_rcp_f32_e32 v64, v0
	v_and_b32_e32 v0, 0xffff0000, v234
	v_mul_f32_e32 v0, 0xbfb8aa3b, v0
	v_exp_f32_e32 v0, v0
	s_nop 0
	v_add_f32_e32 v0, 1.0, v0
	v_rcp_f32_e32 v65, v0
	v_lshlrev_b32_e32 v0, 16, v235
	v_mul_f32_e32 v0, 0xbfb8aa3b, v0
	v_exp_f32_e32 v0, v0
	v_pk_fma_f32 v[118:119], v[54:55], v[64:65], v[118:119]
	v_add_f32_e32 v0, 1.0, v0
	v_rcp_f32_e32 v54, v0
	v_and_b32_e32 v0, 0xffff0000, v235
	v_mul_f32_e32 v0, 0xbfb8aa3b, v0
	v_exp_f32_e32 v0, v0
	s_nop 0
	v_add_f32_e32 v0, 1.0, v0
	v_rcp_f32_e32 v55, v0
	s_nop 0
	v_pk_fma_f32 v[120:121], v[56:57], v[54:55], v[120:121]
	s_waitcnt vmcnt(0)
	v_lshlrev_b32_e32 v0, 16, v236
	v_mul_f32_e32 v0, 0xbfb8aa3b, v0
	v_exp_f32_e32 v0, v0
	s_nop 0
	v_add_f32_e32 v0, 1.0, v0
	v_rcp_f32_e32 v56, v0
	v_and_b32_e32 v0, 0xffff0000, v236
	v_mul_f32_e32 v0, 0xbfb8aa3b, v0
	v_exp_f32_e32 v0, v0
	s_nop 0
	v_add_f32_e32 v0, 1.0, v0
	v_rcp_f32_e32 v57, v0
	v_lshlrev_b32_e32 v0, 16, v237
	v_mul_f32_e32 v0, 0xbfb8aa3b, v0
	v_exp_f32_e32 v0, v0
	v_pk_fma_f32 v[114:115], v[50:51], v[56:57], v[114:115]
	v_add_f32_e32 v0, 1.0, v0
	v_rcp_f32_e32 v50, v0
	v_and_b32_e32 v0, 0xffff0000, v237
	v_mul_f32_e32 v0, 0xbfb8aa3b, v0
	v_exp_f32_e32 v0, v0
	s_nop 0
	v_add_f32_e32 v0, 1.0, v0
	v_rcp_f32_e32 v51, v0
	s_nop 0
	v_pk_fma_f32 v[116:117], v[52:53], v[50:51], v[116:117]
	v_or_b32_e32 v50, 16, v58
	v_ashrrev_i32_e32 v51, 31, v50
	v_lshlrev_b64 v[50:51], 15, v[50:51]
	v_lshl_add_u64 v[50:51], s[86:87], 0, v[50:51]
	v_lshl_add_u64 v[50:51], v[50:51], 0, s[92:93]
	v_lshl_add_u64 v[52:53], v[50:51], 0, v[60:61]
	v_lshl_add_u64 v[50:51], v[52:53], 0, s[20:21]
	v_add_co_u32_e32 v52, vcc, s4, v52
	s_nop 1
	v_addc_co_u32_e32 v53, vcc, 0, v53, vcc
	global_load_dwordx2 v[52:53], v[52:53], off offset:2048
	global_load_dwordx2 v[232:233], v[50:51], off offset:32
	global_load_dwordx2 v[234:235], v[50:51], off offset:64
	global_load_dwordx2 v[236:237], v[50:51], off offset:96
	s_waitcnt vmcnt(3)
	v_lshlrev_b32_e32 v0, 16, v52
	v_mul_f32_e32 v0, 0xbfb8aa3b, v0
	v_exp_f32_e32 v0, v0
	s_nop 0
	v_add_f32_e32 v0, 1.0, v0
	v_rcp_f32_e32 v54, v0
	v_and_b32_e32 v0, 0xffff0000, v52
	v_mul_f32_e32 v0, 0xbfb8aa3b, v0
	v_exp_f32_e32 v0, v0
	s_nop 0
	v_add_f32_e32 v0, 1.0, v0
	v_rcp_f32_e32 v55, v0
	v_lshlrev_b32_e32 v0, 16, v53
	v_mul_f32_e32 v0, 0xbfb8aa3b, v0
	v_exp_f32_e32 v0, v0
	v_pk_fma_f32 v[110:111], v[46:47], v[54:55], v[110:111]
	v_add_f32_e32 v0, 1.0, v0
	v_rcp_f32_e32 v46, v0
	v_and_b32_e32 v0, 0xffff0000, v53
	v_mul_f32_e32 v0, 0xbfb8aa3b, v0
	v_exp_f32_e32 v0, v0
	s_nop 0
	v_add_f32_e32 v0, 1.0, v0
	v_rcp_f32_e32 v47, v0
	s_nop 0
	v_pk_fma_f32 v[112:113], v[48:49], v[46:47], v[112:113]
	s_waitcnt vmcnt(2)
	v_lshlrev_b32_e32 v0, 16, v232
	v_mul_f32_e32 v0, 0xbfb8aa3b, v0
	v_exp_f32_e32 v0, v0
	s_nop 0
	v_add_f32_e32 v0, 1.0, v0
	v_rcp_f32_e32 v48, v0
	v_and_b32_e32 v0, 0xffff0000, v232
	v_mul_f32_e32 v0, 0xbfb8aa3b, v0
	v_exp_f32_e32 v0, v0
	s_nop 0
	v_add_f32_e32 v0, 1.0, v0
	v_rcp_f32_e32 v49, v0
	v_lshlrev_b32_e32 v0, 16, v233
	v_mul_f32_e32 v0, 0xbfb8aa3b, v0
	v_exp_f32_e32 v0, v0
	v_pk_fma_f32 v[106:107], v[42:43], v[48:49], v[106:107]
	v_add_f32_e32 v0, 1.0, v0
	v_rcp_f32_e32 v42, v0
	v_and_b32_e32 v0, 0xffff0000, v233
	v_mul_f32_e32 v0, 0xbfb8aa3b, v0
	v_exp_f32_e32 v0, v0
	s_nop 0
	v_add_f32_e32 v0, 1.0, v0
	v_rcp_f32_e32 v43, v0
	s_nop 0
	v_pk_fma_f32 v[108:109], v[44:45], v[42:43], v[108:109]
	s_waitcnt vmcnt(1)
; __device__ __forceinline__ float sigmoidf_(float x) { return __builtin_amdgcn_rcpf(1.f + __expf(-x)); }
; __device__ void ph_gemm_merge(const Params& p, int l, char* smem) {
;     ...
; #pragma unroll
;       for (int m = 0; m < 4; ++m) {
;         int row = mt * 128 + wr * 64 + m * 16 + fr;
; #pragma unroll
;         for (int n = 0; n < 4; ++n) {
;           int col = nt * 128 + wc * 64 + n * 16 + fq * 4;
;           uint2 gr = *(const uint2*)(p.proj + (long)row * PLD + C_GATE + i * 1024 + col);
;           tot[m][n][0] += sigmoidf_(__uint_as_float(gr.x << 16)) * acc[m][n][0];
;           tot[m][n][1] += sigmoidf_(__uint_as_float(gr.x & 0xffff0000u)) * acc[m][n][1];
;           tot[m][n][2] += sigmoidf_(__uint_as_float(gr.y << 16)) * acc[m][n][2];
;           tot[m][n][3] += sigmoidf_(__uint_as_float(gr.y & 0xffff0000u)) * acc[m][n][3];
;         }
	v_lshlrev_b32_e32 v0, 16, v234
	v_mul_f32_e32 v0, 0xbfb8aa3b, v0
	v_exp_f32_e32 v0, v0
	s_nop 0
	v_add_f32_e32 v0, 1.0, v0
	v_rcp_f32_e32 v44, v0
	v_and_b32_e32 v0, 0xffff0000, v234
	v_mul_f32_e32 v0, 0xbfb8aa3b, v0
	v_exp_f32_e32 v0, v0
	s_nop 0
	v_add_f32_e32 v0, 1.0, v0
	v_rcp_f32_e32 v45, v0
	v_lshlrev_b32_e32 v0, 16, v235
	v_mul_f32_e32 v0, 0xbfb8aa3b, v0
	v_exp_f32_e32 v0, v0
	v_pk_fma_f32 v[102:103], v[38:39], v[44:45], v[102:103]
	v_add_f32_e32 v0, 1.0, v0
	v_rcp_f32_e32 v38, v0
	v_and_b32_e32 v0, 0xffff0000, v235
	v_mul_f32_e32 v0, 0xbfb8aa3b, v0
	v_exp_f32_e32 v0, v0
	s_nop 0
	v_add_f32_e32 v0, 1.0, v0
	v_rcp_f32_e32 v39, v0
	s_nop 0
	v_pk_fma_f32 v[104:105], v[40:41], v[38:39], v[104:105]
	s_waitcnt vmcnt(0)
	v_lshlrev_b32_e32 v0, 16, v236
	v_mul_f32_e32 v0, 0xbfb8aa3b, v0
	v_exp_f32_e32 v0, v0
	s_nop 0
	v_add_f32_e32 v0, 1.0, v0
	v_rcp_f32_e32 v40, v0
	v_and_b32_e32 v0, 0xffff0000, v236
	v_mul_f32_e32 v0, 0xbfb8aa3b, v0
	v_exp_f32_e32 v0, v0
	s_nop 0
	v_add_f32_e32 v0, 1.0, v0
	v_rcp_f32_e32 v41, v0
	v_lshlrev_b32_e32 v0, 16, v237
	v_mul_f32_e32 v0, 0xbfb8aa3b, v0
	v_exp_f32_e32 v0, v0
	v_pk_fma_f32 v[98:99], v[34:35], v[40:41], v[98:99]
	v_add_f32_e32 v0, 1.0, v0
	v_rcp_f32_e32 v34, v0
	v_and_b32_e32 v0, 0xffff0000, v237
	v_mul_f32_e32 v0, 0xbfb8aa3b, v0
	v_exp_f32_e32 v0, v0
	s_nop 0
	v_add_f32_e32 v0, 1.0, v0
	v_rcp_f32_e32 v35, v0
	s_nop 0
	v_pk_fma_f32 v[100:101], v[36:37], v[34:35], v[100:101]
	v_or_b32_e32 v34, 32, v58
	v_ashrrev_i32_e32 v35, 31, v34
	v_lshlrev_b64 v[34:35], 15, v[34:35]
	v_lshl_add_u64 v[34:35], s[86:87], 0, v[34:35]
	v_lshl_add_u64 v[34:35], v[34:35], 0, s[92:93]
	v_lshl_add_u64 v[36:37], v[34:35], 0, v[60:61]
	v_lshl_add_u64 v[34:35], v[36:37], 0, s[20:21]
	v_add_co_u32_e32 v36, vcc, s4, v36
	s_nop 1
	v_addc_co_u32_e32 v37, vcc, 0, v37, vcc
	global_load_dwordx2 v[36:37], v[36:37], off offset:2048
	global_load_dwordx2 v[232:233], v[34:35], off offset:32
	global_load_dwordx2 v[234:235], v[34:35], off offset:64
	global_load_dwordx2 v[236:237], v[34:35], off offset:96
	s_waitcnt vmcnt(3)
	v_lshlrev_b32_e32 v0, 16, v36
	v_mul_f32_e32 v0, 0xbfb8aa3b, v0
	v_exp_f32_e32 v0, v0
	s_nop 0
	v_add_f32_e32 v0, 1.0, v0
	v_rcp_f32_e32 v38, v0
	v_and_b32_e32 v0, 0xffff0000, v36
	v_mul_f32_e32 v0, 0xbfb8aa3b, v0
	v_exp_f32_e32 v0, v0
	s_nop 0
	v_add_f32_e32 v0, 1.0, v0
	v_rcp_f32_e32 v39, v0
	v_lshlrev_b32_e32 v0, 16, v37
	v_mul_f32_e32 v0, 0xbfb8aa3b, v0
	v_exp_f32_e32 v0, v0
	v_pk_fma_f32 v[94:95], v[30:31], v[38:39], v[94:95]
	v_add_f32_e32 v0, 1.0, v0
	v_rcp_f32_e32 v30, v0
	v_and_b32_e32 v0, 0xffff0000, v37
	v_mul_f32_e32 v0, 0xbfb8aa3b, v0
	v_exp_f32_e32 v0, v0
	s_nop 0
	v_add_f32_e32 v0, 1.0, v0
	v_rcp_f32_e32 v31, v0
	s_nop 0
	v_pk_fma_f32 v[96:97], v[32:33], v[30:31], v[96:97]
	s_waitcnt vmcnt(2)
	v_lshlrev_b32_e32 v0, 16, v232
	v_mul_f32_e32 v0, 0xbfb8aa3b, v0
	v_exp_f32_e32 v0, v0
	s_nop 0
	v_add_f32_e32 v0, 1.0, v0
	v_rcp_f32_e32 v32, v0
	v_and_b32_e32 v0, 0xffff0000, v232
	v_mul_f32_e32 v0, 0xbfb8aa3b, v0
	v_exp_f32_e32 v0, v0
	s_nop 0
	v_add_f32_e32 v0, 1.0, v0
	v_rcp_f32_e32 v33, v0
	v_lshlrev_b32_e32 v0, 16, v233
	v_mul_f32_e32 v0, 0xbfb8aa3b, v0
	v_exp_f32_e32 v0, v0
	v_pk_fma_f32 v[90:91], v[26:27], v[32:33], v[90:91]
	v_add_f32_e32 v0, 1.0, v0
	v_rcp_f32_e32 v26, v0
	v_and_b32_e32 v0, 0xffff0000, v233
	v_mul_f32_e32 v0, 0xbfb8aa3b, v0
	v_exp_f32_e32 v0, v0
	s_nop 0
	v_add_f32_e32 v0, 1.0, v0
	v_rcp_f32_e32 v27, v0
	s_nop 0
	v_pk_fma_f32 v[92:93], v[28:29], v[26:27], v[92:93]
	s_waitcnt vmcnt(1)
	v_lshlrev_b32_e32 v0, 16, v234
	v_mul_f32_e32 v0, 0xbfb8aa3b, v0
	v_exp_f32_e32 v0, v0
	s_nop 0
	v_add_f32_e32 v0, 1.0, v0
	v_rcp_f32_e32 v28, v0
	v_and_b32_e32 v0, 0xffff0000, v234
	v_mul_f32_e32 v0, 0xbfb8aa3b, v0
	v_exp_f32_e32 v0, v0
	s_nop 0
	v_add_f32_e32 v0, 1.0, v0
	v_rcp_f32_e32 v29, v0
	v_lshlrev_b32_e32 v0, 16, v235
	v_mul_f32_e32 v0, 0xbfb8aa3b, v0
	v_exp_f32_e32 v0, v0
	v_pk_fma_f32 v[86:87], v[22:23], v[28:29], v[86:87]
	v_add_f32_e32 v0, 1.0, v0
	v_rcp_f32_e32 v22, v0
	v_and_b32_e32 v0, 0xffff0000, v235
	v_mul_f32_e32 v0, 0xbfb8aa3b, v0
	v_exp_f32_e32 v0, v0
	s_nop 0
	v_add_f32_e32 v0, 1.0, v0
	v_rcp_f32_e32 v23, v0
	s_nop 0
	v_pk_fma_f32 v[88:89], v[24:25], v[22:23], v[88:89]
	s_waitcnt vmcnt(0)
	v_lshlrev_b32_e32 v0, 16, v236
	v_mul_f32_e32 v0, 0xbfb8aa3b, v0
	v_exp_f32_e32 v0, v0
	s_nop 0
	v_add_f32_e32 v0, 1.0, v0
	v_rcp_f32_e32 v24, v0
	v_and_b32_e32 v0, 0xffff0000, v236
	v_mul_f32_e32 v0, 0xbfb8aa3b, v0
	v_exp_f32_e32 v0, v0
	s_nop 0
	v_add_f32_e32 v0, 1.0, v0
	v_rcp_f32_e32 v25, v0
	v_lshlrev_b32_e32 v0, 16, v237
	v_mul_f32_e32 v0, 0xbfb8aa3b, v0
	v_exp_f32_e32 v0, v0
	v_pk_fma_f32 v[82:83], v[18:19], v[24:25], v[82:83]
	v_add_f32_e32 v0, 1.0, v0
	v_rcp_f32_e32 v18, v0
	v_and_b32_e32 v0, 0xffff0000, v237
	v_mul_f32_e32 v0, 0xbfb8aa3b, v0
	v_exp_f32_e32 v0, v0
	s_nop 0
	v_add_f32_e32 v0, 1.0, v0
	v_rcp_f32_e32 v19, v0
	s_nop 0
	v_pk_fma_f32 v[84:85], v[20:21], v[18:19], v[84:85]
	v_or_b32_e32 v18, 48, v58
	v_ashrrev_i32_e32 v19, 31, v18
	v_lshlrev_b64 v[18:19], 15, v[18:19]
	v_lshl_add_u64 v[18:19], s[86:87], 0, v[18:19]
	v_lshl_add_u64 v[18:19], v[18:19], 0, s[92:93]
	v_lshl_add_u64 v[20:21], v[18:19], 0, v[60:61]
	v_lshl_add_u64 v[18:19], v[20:21], 0, s[20:21]
	v_add_co_u32_e32 v20, vcc, s4, v20
	s_nop 1
	v_addc_co_u32_e32 v21, vcc, 0, v21, vcc
	global_load_dwordx2 v[20:21], v[20:21], off offset:2048
	global_load_dwordx2 v[232:233], v[18:19], off offset:32
	global_load_dwordx2 v[234:235], v[18:19], off offset:64
	global_load_dwordx2 v[236:237], v[18:19], off offset:96
	s_waitcnt vmcnt(3)
; __device__ __forceinline__ float sigmoidf_(float x) { return __builtin_amdgcn_rcpf(1.f + __expf(-x)); }
; __device__ __forceinline__ int otid() { int t = threadIdx.x; asm volatile("" : "+v"(t)); return t; }
; __device__ void ph_gemm_merge(const Params& p, int l, char* smem) {
;     ...
; #pragma unroll
;       for (int m = 0; m < 4; ++m) {
;         int row = mt * 128 + wr * 64 + m * 16 + fr;
; #pragma unroll
;         for (int n = 0; n < 4; ++n) {
;           int col = nt * 128 + wc * 64 + n * 16 + fq * 4;
;           uint2 gr = *(const uint2*)(p.proj + (long)row * PLD + C_GATE + i * 1024 + col);
;           tot[m][n][0] += sigmoidf_(__uint_as_float(gr.x << 16)) * acc[m][n][0];
;           tot[m][n][1] += sigmoidf_(__uint_as_float(gr.x & 0xffff0000u)) * acc[m][n][1];
;           tot[m][n][2] += sigmoidf_(__uint_as_float(gr.y << 16)) * acc[m][n][2];
;           tot[m][n][3] += sigmoidf_(__uint_as_float(gr.y & 0xffff0000u)) * acc[m][n][3];
;         }
;       }
;     }
;     const int tid3 = otid();
;     const int wr = (tid3 >> 7) & 1, wc = (tid3 >> 6) & 1, fr = tid3 & 15, fq = (tid3 >> 4) & 3;
; #pragma unroll
;     for (int m = 0; m < 4; ++m) {
;       int row = mt * 128 + wr * 64 + m * 16 + fr;
; #pragma unroll
;       for (int n = 0; n < 4; ++n) {
;         int col = nt * 128 + wc * 64 + n * 16 + fq * 4;
;         uint2 o; o.x = pack2(tot[m][n][0], tot[m][n][1]); o.y = pack2(tot[m][n][2], tot[m][n][3]);
;         *(uint2*)(p.obuf + (long)TG * 3072 + (long)row * D + col) = o;
;       }
;     }
	v_lshlrev_b32_e32 v0, 16, v20
	v_mul_f32_e32 v0, 0xbfb8aa3b, v0
	v_exp_f32_e32 v0, v0
	s_nop 0
	v_add_f32_e32 v0, 1.0, v0
	v_rcp_f32_e32 v22, v0
	v_and_b32_e32 v0, 0xffff0000, v20
	v_mul_f32_e32 v0, 0xbfb8aa3b, v0
	v_exp_f32_e32 v0, v0
	s_nop 0
	v_add_f32_e32 v0, 1.0, v0
	v_rcp_f32_e32 v23, v0
	v_lshlrev_b32_e32 v0, 16, v21
	v_mul_f32_e32 v0, 0xbfb8aa3b, v0
	v_exp_f32_e32 v0, v0
	v_pk_fma_f32 v[78:79], v[14:15], v[22:23], v[78:79]
	v_add_f32_e32 v0, 1.0, v0
	v_rcp_f32_e32 v14, v0
	v_and_b32_e32 v0, 0xffff0000, v21
	v_mul_f32_e32 v0, 0xbfb8aa3b, v0
	v_exp_f32_e32 v0, v0
	s_nop 0
	v_add_f32_e32 v0, 1.0, v0
	v_rcp_f32_e32 v15, v0
	s_nop 0
	v_pk_fma_f32 v[80:81], v[16:17], v[14:15], v[80:81]
	s_waitcnt vmcnt(2)
	v_lshlrev_b32_e32 v0, 16, v232
	v_mul_f32_e32 v0, 0xbfb8aa3b, v0
	v_exp_f32_e32 v0, v0
	s_nop 0
	v_add_f32_e32 v0, 1.0, v0
	v_rcp_f32_e32 v16, v0
	v_and_b32_e32 v0, 0xffff0000, v232
	v_mul_f32_e32 v0, 0xbfb8aa3b, v0
	v_exp_f32_e32 v0, v0
	s_nop 0
	v_add_f32_e32 v0, 1.0, v0
	v_rcp_f32_e32 v17, v0
	v_lshlrev_b32_e32 v0, 16, v233
	v_mul_f32_e32 v0, 0xbfb8aa3b, v0
	v_exp_f32_e32 v0, v0
	v_pk_fma_f32 v[74:75], v[10:11], v[16:17], v[74:75]
	v_add_f32_e32 v0, 1.0, v0
	v_rcp_f32_e32 v10, v0
	v_and_b32_e32 v0, 0xffff0000, v233
	v_mul_f32_e32 v0, 0xbfb8aa3b, v0
	v_exp_f32_e32 v0, v0
	s_nop 0
	v_add_f32_e32 v0, 1.0, v0
	v_rcp_f32_e32 v11, v0
	s_nop 0
	v_pk_fma_f32 v[76:77], v[12:13], v[10:11], v[76:77]
	s_waitcnt vmcnt(1)
	v_lshlrev_b32_e32 v0, 16, v234
	v_mul_f32_e32 v0, 0xbfb8aa3b, v0
	v_exp_f32_e32 v0, v0
	s_nop 0
	v_add_f32_e32 v0, 1.0, v0
	v_rcp_f32_e32 v12, v0
	v_and_b32_e32 v0, 0xffff0000, v234
	v_mul_f32_e32 v0, 0xbfb8aa3b, v0
	v_exp_f32_e32 v0, v0
	s_nop 0
	v_add_f32_e32 v0, 1.0, v0
	v_rcp_f32_e32 v13, v0
	v_lshlrev_b32_e32 v0, 16, v235
	v_mul_f32_e32 v0, 0xbfb8aa3b, v0
	v_exp_f32_e32 v0, v0
	v_pk_fma_f32 v[70:71], v[6:7], v[12:13], v[70:71]
	v_add_f32_e32 v0, 1.0, v0
	v_rcp_f32_e32 v6, v0
	v_and_b32_e32 v0, 0xffff0000, v235
	v_mul_f32_e32 v0, 0xbfb8aa3b, v0
	v_exp_f32_e32 v0, v0
	s_nop 0
	v_add_f32_e32 v0, 1.0, v0
	v_rcp_f32_e32 v7, v0
	s_nop 0
	v_pk_fma_f32 v[72:73], v[8:9], v[6:7], v[72:73]
	s_waitcnt vmcnt(0)
	v_lshlrev_b32_e32 v0, 16, v236
	v_mul_f32_e32 v0, 0xbfb8aa3b, v0
	v_exp_f32_e32 v0, v0
	s_nop 0
	v_add_f32_e32 v0, 1.0, v0
	v_rcp_f32_e32 v8, v0
	v_and_b32_e32 v0, 0xffff0000, v236
	v_mul_f32_e32 v0, 0xbfb8aa3b, v0
	v_exp_f32_e32 v0, v0
	s_nop 0
	v_add_f32_e32 v0, 1.0, v0
	v_rcp_f32_e32 v9, v0
	v_lshlrev_b32_e32 v0, 16, v237
	v_mul_f32_e32 v0, 0xbfb8aa3b, v0
	v_exp_f32_e32 v0, v0
	v_pk_fma_f32 v[66:67], v[2:3], v[8:9], v[66:67]
	v_add_f32_e32 v0, 1.0, v0
	v_rcp_f32_e32 v2, v0
	v_and_b32_e32 v0, 0xffff0000, v237
	v_mul_f32_e32 v0, 0xbfb8aa3b, v0
	v_exp_f32_e32 v0, v0
	s_nop 0
	v_add_f32_e32 v0, 1.0, v0
	v_rcp_f32_e32 v3, v0
	s_nop 0
	v_pk_fma_f32 v[68:69], v[4:5], v[2:3], v[68:69]
	s_cbranch_scc0 .LBB0_997
	v_mov_b32_e32 v0, v156
	v_readlane_b32 s12, v241, 17
	v_lshrrev_b32_e32 v4, 1, v0
	v_and_b32_e32 v3, 64, v0
	v_and_b32_e32 v2, 15, v0
	v_and_b32_e32 v4, 64, v4
	v_lshrrev_b32_e32 v0, 2, v0
	v_or3_b32 v2, v2, v4, s67
	v_and_b32_e32 v0, 12, v0
	v_or3_b32 v4, v3, v0, s66
	v_ashrrev_i32_e32 v3, 31, v2
	v_lshlrev_b64 v[6:7], 11, v[2:3]
	v_readlane_b32 s13, v241, 18
	v_ashrrev_i32_e32 v5, 31, v4
	v_lshlrev_b64 v[4:5], 1, v[4:5]
	v_lshl_add_u64 v[6:7], s[12:13], 0, v[6:7]
	v_cvt_pk_bf16_f32 v8, v126, v127
	v_cvt_pk_bf16_f32 v9, v128, v129
	v_lshl_add_u64 v[6:7], v[6:7], 0, v[4:5]
	global_store_dwordx2 v[6:7], v[8:9], off
	v_cvt_pk_bf16_f32 v8, v122, v123
	v_cvt_pk_bf16_f32 v9, v124, v125
	global_store_dwordx2 v[6:7], v[8:9], off offset:32
	v_cvt_pk_bf16_f32 v8, v118, v119
	v_cvt_pk_bf16_f32 v9, v120, v121
	global_store_dwordx2 v[6:7], v[8:9], off offset:64
	v_cvt_pk_bf16_f32 v8, v114, v115
	v_cvt_pk_bf16_f32 v9, v116, v117
	global_store_dwordx2 v[6:7], v[8:9], off offset:96
	v_or_b32_e32 v6, 16, v2
	v_ashrrev_i32_e32 v7, 31, v6
	v_lshlrev_b64 v[6:7], 11, v[6:7]
	v_lshl_add_u64 v[6:7], s[12:13], 0, v[6:7]
	v_cvt_pk_bf16_f32 v8, v110, v111
	v_cvt_pk_bf16_f32 v9, v112, v113
	v_lshl_add_u64 v[6:7], v[6:7], 0, v[4:5]
	global_store_dwordx2 v[6:7], v[8:9], off
	v_cvt_pk_bf16_f32 v8, v106, v107
	v_cvt_pk_bf16_f32 v9, v108, v109
	global_store_dwordx2 v[6:7], v[8:9], off offset:32
	v_cvt_pk_bf16_f32 v8, v102, v103
	v_cvt_pk_bf16_f32 v9, v104, v105
	global_store_dwordx2 v[6:7], v[8:9], off offset:64
	v_cvt_pk_bf16_f32 v8, v98, v99
	v_cvt_pk_bf16_f32 v9, v100, v101
	global_store_dwordx2 v[6:7], v[8:9], off offset:96
	v_or_b32_e32 v6, 32, v2
	v_ashrrev_i32_e32 v7, 31, v6
	v_lshlrev_b64 v[6:7], 11, v[6:7]
	v_or_b32_e32 v2, 48, v2
	v_lshl_add_u64 v[6:7], s[12:13], 0, v[6:7]
	v_ashrrev_i32_e32 v3, 31, v2
	v_cvt_pk_bf16_f32 v8, v94, v95
	v_cvt_pk_bf16_f32 v9, v96, v97
	v_lshl_add_u64 v[6:7], v[6:7], 0, v[4:5]
	v_lshlrev_b64 v[2:3], 11, v[2:3]
	global_store_dwordx2 v[6:7], v[8:9], off
	v_cvt_pk_bf16_f32 v8, v90, v91
	v_cvt_pk_bf16_f32 v9, v92, v93
	v_lshl_add_u64 v[2:3], s[12:13], 0, v[2:3]
	global_store_dwordx2 v[6:7], v[8:9], off offset:32
	v_cvt_pk_bf16_f32 v8, v86, v87
	v_cvt_pk_bf16_f32 v9, v88, v89
	v_lshl_add_u64 v[2:3], v[2:3], 0, v[4:5]
	v_cvt_pk_bf16_f32 v4, v74, v75
	v_cvt_pk_bf16_f32 v5, v76, v77
	v_readlane_b32 s58, v240, 18
	global_store_dwordx2 v[6:7], v[8:9], off offset:64
	v_cvt_pk_bf16_f32 v8, v82, v83
	v_cvt_pk_bf16_f32 v9, v84, v85
	global_store_dwordx2 v[2:3], v[4:5], off offset:32
	v_cvt_pk_bf16_f32 v4, v70, v71
	v_cvt_pk_bf16_f32 v5, v72, v73
	v_readlane_b32 s59, v240, 19
	global_store_dwordx2 v[6:7], v[8:9], off offset:96
	v_cvt_pk_bf16_f32 v6, v78, v79
	v_cvt_pk_bf16_f32 v7, v80, v81
	global_store_dwordx2 v[2:3], v[4:5], off offset:64
	v_cvt_pk_bf16_f32 v4, v66, v67
	v_cvt_pk_bf16_f32 v5, v68, v69
	s_movk_i32 s14, 0x3000
	s_mov_b32 s59, 0x38e38e39
	global_store_dwordx2 v[2:3], v[6:7], off
	global_store_dwordx2 v[2:3], v[4:5], off offset:96
	s_branch .LBB0_994

; __device__ void ph_gemm_out(const Params& p, int l, int g, char* smem) {
;     ...
; #pragma unroll
;     for (int m = 0; m < 4; ++m) {
;       int row = mt * 128 + wr * 64 + m * 16 + fr;
;       int bl = row / TPB, pp = row % TPB, b = g * GB + bl;
;       const float* src; float* dst; int mrow;
;       if (pp < CTX) { src = p.ctx + ((long)b * CTX + pp) * D; dst = p.ctxs + ((long)b * CTX + pp) * D; mrow = 16; }
;       else { long off = ((long)b * SEQ + (pp - CTX)) * D; src = (l == 0 ? p.x : p.out) + off; dst = p.out + off; mrow = b; }
;       const float* gt = p.mod + ((long)l * 17 + mrow) * 3072 + 2048;
; #pragma unroll
;       for (int n = 0; n < 4; ++n) {
;         int col = nt * 128 + wc * 64 + n * 16 + fq * 4;
;         float4 xv = *(const float4*)(src + col), gv = *(const float4*)(gt + col);
;         float4 o;
;         o.x = xv.x + gv.x * acc[m][n][0]; o.y = xv.y + gv.y * acc[m][n][1];
;         o.z = xv.z + gv.z * acc[m][n][2]; o.w = xv.w + gv.w * acc[m][n][3];
;         *(float4*)(dst + col) = o;
;       }
;     }
.LBB0_1055:
	s_or_b64 exec, exec, s[40:41]
	v_lshlrev_b64 v[24:25], v28, v[24:25]
	v_lshlrev_b64 v[18:19], 10, v[18:19]
	v_lshl_add_u64 v[18:19], v[24:25], 0, v[18:19]
	v_readlane_b32 s12, v240, 35
	v_lshlrev_b64 v[18:19], 2, v[18:19]
	v_readlane_b32 s13, v240, 36
	v_lshl_add_u64 v[22:23], v[22:23], 0, v[18:19]
	v_lshl_add_u64 v[18:19], v[20:21], 0, v[18:19]
	v_lshl_add_u64 v[20:21], v[26:27], 0, s[12:13]
	v_mov_b64_e32 v[24:25], s[90:91]
	v_mad_u64_u32 v[24:25], s[40:41], v20, s14, v[24:25]
	v_mad_i32_i24 v25, v21, s14, v25
	s_mov_b64 s[12:13], 0x2000
	v_lshl_add_u64 v[26:27], v[24:25], 0, s[12:13]
	v_lshl_add_u64 v[28:29], v[22:23], 0, v[66:67]
	v_lshl_add_u64 v[22:23], v[26:27], 0, v[66:67]
	v_lshl_add_u64 v[30:31], v[18:19], 0, v[66:67]
	global_load_dwordx4 v[18:21], v[28:29], off
	s_nop 0
	v_mov_b64_e32 v[232:233], v[22:23]
	global_load_dwordx4 v[22:25], v[22:23], off
	global_load_dwordx4 v[200:203], v[28:29], off offset:64
	global_load_dwordx4 v[204:207], v[232:233], off offset:64
	global_load_dwordx4 v[208:211], v[28:29], off offset:128
	global_load_dwordx4 v[212:215], v[232:233], off offset:128
	global_load_dwordx4 v[216:219], v[28:29], off offset:192
	global_load_dwordx4 v[220:223], v[232:233], off offset:192
	s_waitcnt vmcnt(6)
	v_pk_fma_f32 v[14:15], v[14:15], v[22:23], v[18:19]
	v_pk_fma_f32 v[16:17], v[16:17], v[24:25], v[20:21]
	global_store_dwordx4 v[30:31], v[14:17], off
	v_lshl_add_u64 v[18:19], v[62:63], 2, v[26:27]
	s_nop 0
	s_waitcnt vmcnt(5)
	v_pk_fma_f32 v[10:11], v[10:11], v[204:205], v[200:201]
	v_pk_fma_f32 v[12:13], v[12:13], v[206:207], v[202:203]
	global_store_dwordx4 v[30:31], v[10:13], off offset:64
	v_lshl_add_u64 v[14:15], v[58:59], 2, v[26:27]
	s_nop 0
	s_waitcnt vmcnt(4)
	v_pk_fma_f32 v[6:7], v[6:7], v[212:213], v[208:209]
	v_pk_fma_f32 v[8:9], v[8:9], v[214:215], v[210:211]
	global_store_dwordx4 v[30:31], v[6:9], off offset:128
	v_lshl_add_u64 v[10:11], v[54:55], 2, v[26:27]
	s_nop 0
	s_waitcnt vmcnt(3)
	v_pk_fma_f32 v[2:3], v[2:3], v[220:221], v[216:217]
	v_pk_fma_f32 v[4:5], v[4:5], v[222:223], v[218:219]
	global_store_dwordx4 v[30:31], v[2:5], off offset:192

; __device__ void ph_gemm_out(const Params& p, int l, int g, char* smem) {
;     ...
; #pragma unroll
;     for (int m = 0; m < 4; ++m) {
;       int row = mt * 128 + wr * 64 + m * 16 + fr;
;       int bl = row / TPB, pp = row % TPB, b = g * GB + bl;
;       const float* src; float* dst; int mrow;
;       if (pp < CTX) { src = p.ctx + ((long)b * CTX + pp) * D; dst = p.ctxs + ((long)b * CTX + pp) * D; mrow = 16; }
;       else { long off = ((long)b * SEQ + (pp - CTX)) * D; src = (l == 0 ? p.x : p.out) + off; dst = p.out + off; mrow = b; }
;       const float* gt = p.mod + ((long)l * 17 + mrow) * 3072 + 2048;
; #pragma unroll
;       for (int n = 0; n < 4; ++n) {
;         int col = nt * 128 + wc * 64 + n * 16 + fq * 4;
;         float4 xv = *(const float4*)(src + col), gv = *(const float4*)(gt + col);
;         float4 o;
;         o.x = xv.x + gv.x * acc[m][n][0]; o.y = xv.y + gv.y * acc[m][n][1];
;         o.z = xv.z + gv.z * acc[m][n][2]; o.w = xv.w + gv.w * acc[m][n][3];
;         *(float4*)(dst + col) = o;
;       }
;     }
.LBB0_1062:
	s_or_saveexec_b64 s[42:43], s[42:43]
	v_add_u32_e32 v72, s44, v72
	v_ashrrev_i32_e32 v73, 31, v72
	v_mov_b64_e32 v[76:77], 21
	v_mov_b64_e32 v[74:75], v[72:73]
	s_xor_b64 exec, exec, s[42:43]
	v_ashrrev_i32_e32 v69, 31, v68
	v_mov_b64_e32 v[74:75], 16
	v_mov_b64_e32 v[76:77], 18
	s_or_b64 exec, exec, s[42:43]
	v_lshlrev_b64 v[72:73], v76, v[72:73]
	v_lshlrev_b64 v[68:69], 10, v[68:69]
	v_lshl_add_u64 v[68:69], v[72:73], 0, v[68:69]
	v_readlane_b32 s12, v240, 35
	v_lshrrev_b32_e32 v77, 2, v79
	v_lshlrev_b64 v[68:69], 2, v[68:69]
	v_readlane_b32 s13, v240, 36
	v_and_b32_e32 v0, 64, v79
	s_lshl_b32 s40, s40, 7
	v_and_b32_e32 v77, 12, v77
	v_lshl_add_u64 v[70:71], v[70:71], 0, v[68:69]
	v_lshl_add_u64 v[68:69], v[66:67], 0, v[68:69]
	v_lshl_add_u64 v[66:67], v[74:75], 0, s[12:13]
	v_mov_b64_e32 v[72:73], s[90:91]
	v_or3_b32 v80, v0, s40, v77
	v_mad_u64_u32 v[72:73], s[40:41], v66, s14, v[72:73]
	v_ashrrev_i32_e32 v81, 31, v80
	v_mad_i32_i24 v73, v67, s14, v73
	s_mov_b64 s[12:13], 0x2000
	v_lshl_add_u64 v[76:77], v[72:73], 0, s[12:13]
	v_lshlrev_b64 v[66:67], 2, v[80:81]
	v_lshl_add_u64 v[82:83], v[70:71], 0, v[66:67]
	v_lshl_add_u64 v[72:73], v[76:77], 0, v[66:67]
	v_lshl_add_u64 v[84:85], v[68:69], 0, v[66:67]
	global_load_dwordx4 v[68:71], v[82:83], off
	s_nop 0
	v_mov_b64_e32 v[232:233], v[72:73]
	global_load_dwordx4 v[72:75], v[72:73], off
	global_load_dwordx4 v[200:203], v[82:83], off offset:64
	global_load_dwordx4 v[204:207], v[232:233], off offset:64
	global_load_dwordx4 v[208:211], v[82:83], off offset:128
	global_load_dwordx4 v[212:215], v[232:233], off offset:128
	global_load_dwordx4 v[216:219], v[82:83], off offset:192
	global_load_dwordx4 v[220:223], v[232:233], off offset:192
	v_or_b32_e32 v0, 16, v78
	v_readlane_b32 s40, v240, 6
	v_readlane_b32 s12, v241, 62
	v_readlane_b32 s42, v240, 8
	v_readlane_b32 s43, v240, 9
	v_readlane_b32 s13, v241, 63
	v_readlane_b32 s41, v240, 7
	s_waitcnt vmcnt(6)
	v_pk_fma_f32 v[62:63], v[62:63], v[72:73], v[68:69]
	v_pk_fma_f32 v[64:65], v[64:65], v[74:75], v[70:71]
	global_store_dwordx4 v[84:85], v[62:65], off
	s_nop 1
	v_or_b32_e32 v62, 16, v80
	v_ashrrev_i32_e32 v63, 31, v62
	v_lshl_add_u64 v[64:65], v[62:63], 2, v[76:77]
	s_waitcnt vmcnt(5)
	v_pk_fma_f32 v[58:59], v[58:59], v[204:205], v[200:201]
	v_pk_fma_f32 v[60:61], v[60:61], v[206:207], v[202:203]
	global_store_dwordx4 v[84:85], v[58:61], off offset:64
	s_nop 1
	v_or_b32_e32 v58, 32, v80
	v_ashrrev_i32_e32 v59, 31, v58
	v_lshl_add_u64 v[60:61], v[58:59], 2, v[76:77]
	s_waitcnt vmcnt(4)
	v_pk_fma_f32 v[54:55], v[54:55], v[212:213], v[208:209]
	v_pk_fma_f32 v[56:57], v[56:57], v[214:215], v[210:211]
	global_store_dwordx4 v[84:85], v[54:57], off offset:128
	s_nop 1
	v_or_b32_e32 v54, 48, v80
	v_ashrrev_i32_e32 v55, 31, v54
	v_lshl_add_u64 v[56:57], v[54:55], 2, v[76:77]
	v_mov_b64_e32 v[56:57], s[12:13]
	s_waitcnt vmcnt(3)
	v_pk_fma_f32 v[50:51], v[50:51], v[220:221], v[216:217]
	v_pk_fma_f32 v[52:53], v[52:53], v[222:223], v[218:219]
	global_store_dwordx4 v[84:85], v[50:53], off offset:192
	s_nop 1
	v_mul_hi_i32 v50, v0, s59
	v_lshrrev_b32_e32 v51, 31, v50
	v_ashrrev_i32_e32 v50, 9, v50
	v_add_u32_e32 v60, v50, v51
	v_mul_i32_i24_e32 v50, 0x900, v60
	v_sub_u32_e32 v50, v0, v50
	v_cmp_lt_i32_e32 vcc, s24, v50
	v_mov_b64_e32 v[52:53], s[42:43]
	s_and_saveexec_b64 s[40:41], vcc
	s_xor_b64 s[40:41], exec, s[40:41]
	s_cbranch_execz .LBB0_1066
	v_readlane_b32 s12, v240, 41
	v_add_u32_e32 v0, 0xffffff00, v50
	v_readlane_b32 s13, v240, 42
	v_mov_b64_e32 v[52:53], s[76:77]
	v_mov_b64_e32 v[50:51], v[0:1]
	v_mov_b64_e32 v[56:57], s[12:13]
; __device__ void ph_gemm_out(const Params& p, int l, int g, char* smem) {
;     ...
; #pragma unroll
;     for (int m = 0; m < 4; ++m) {
;       int row = mt * 128 + wr * 64 + m * 16 + fr;
;       int bl = row / TPB, pp = row % TPB, b = g * GB + bl;
;       const float* src; float* dst; int mrow;
;       if (pp < CTX) { src = p.ctx + ((long)b * CTX + pp) * D; dst = p.ctxs + ((long)b * CTX + pp) * D; mrow = 16; }
;       else { long off = ((long)b * SEQ + (pp - CTX)) * D; src = (l == 0 ? p.x : p.out) + off; dst = p.out + off; mrow = b; }
;       const float* gt = p.mod + ((long)l * 17 + mrow) * 3072 + 2048;
; #pragma unroll
;       for (int n = 0; n < 4; ++n) {
;         int col = nt * 128 + wc * 64 + n * 16 + fq * 4;
;         float4 xv = *(const float4*)(src + col), gv = *(const float4*)(gt + col);
;         float4 o;
;         o.x = xv.x + gv.x * acc[m][n][0]; o.y = xv.y + gv.y * acc[m][n][1];
;         o.z = xv.z + gv.z * acc[m][n][2]; o.w = xv.w + gv.w * acc[m][n][3];
;         *(float4*)(dst + col) = o;
;       }
;     }
.LBB0_1066:
	s_or_saveexec_b64 s[40:41], s[40:41]
	v_add_u32_e32 v60, s44, v60
	v_ashrrev_i32_e32 v61, 31, v60
	v_mov_b64_e32 v[68:69], 21
	v_mov_b64_e32 v[64:65], v[60:61]
	s_xor_b64 exec, exec, s[40:41]
	v_ashrrev_i32_e32 v51, 31, v50
	v_mov_b64_e32 v[64:65], 16
	v_mov_b64_e32 v[68:69], 18
	s_or_b64 exec, exec, s[40:41]
	v_lshlrev_b64 v[60:61], v68, v[60:61]
	v_lshlrev_b64 v[50:51], 10, v[50:51]
	v_lshl_add_u64 v[50:51], v[60:61], 0, v[50:51]
	v_readlane_b32 s12, v240, 35
	v_lshlrev_b64 v[50:51], 2, v[50:51]
	v_readlane_b32 s13, v240, 36
	v_lshl_add_u64 v[56:57], v[56:57], 0, v[50:51]
	v_lshl_add_u64 v[50:51], v[52:53], 0, v[50:51]
	v_lshl_add_u64 v[52:53], v[64:65], 0, s[12:13]
	v_mov_b64_e32 v[60:61], s[90:91]
	v_mad_u64_u32 v[60:61], s[40:41], v52, s14, v[60:61]
	v_mad_i32_i24 v61, v53, s14, v61
	s_mov_b64 s[12:13], 0x2000
	v_lshl_add_u64 v[60:61], v[60:61], 0, s[12:13]
	v_lshl_add_u64 v[56:57], v[56:57], 0, v[66:67]
	v_lshl_add_u64 v[64:65], v[60:61], 0, v[66:67]
	v_lshl_add_u64 v[72:73], v[50:51], 0, v[66:67]
	global_load_dwordx4 v[50:53], v[56:57], off
	v_mov_b64_e32 v[232:233], v[64:65]
	global_load_dwordx4 v[68:71], v[64:65], off
	global_load_dwordx4 v[200:203], v[56:57], off offset:64
	global_load_dwordx4 v[204:207], v[232:233], off offset:64
	global_load_dwordx4 v[208:211], v[56:57], off offset:128
	global_load_dwordx4 v[212:215], v[232:233], off offset:128
	global_load_dwordx4 v[216:219], v[56:57], off offset:192
	global_load_dwordx4 v[220:223], v[232:233], off offset:192
	v_or_b32_e32 v0, 32, v78
	v_readlane_b32 s40, v240, 6
	v_readlane_b32 s12, v241, 62
	v_readlane_b32 s42, v240, 8
	v_readlane_b32 s43, v240, 9
	v_readlane_b32 s13, v241, 63
	v_readlane_b32 s41, v240, 7
	s_waitcnt vmcnt(6)
	v_pk_fma_f32 v[46:47], v[46:47], v[68:69], v[50:51]
	v_pk_fma_f32 v[48:49], v[48:49], v[70:71], v[52:53]
	global_store_dwordx4 v[72:73], v[46:49], off
	v_lshl_add_u64 v[50:51], v[62:63], 2, v[60:61]
	s_nop 0
	s_waitcnt vmcnt(5)
	v_pk_fma_f32 v[42:43], v[42:43], v[204:205], v[200:201]
	v_pk_fma_f32 v[44:45], v[44:45], v[206:207], v[202:203]
	global_store_dwordx4 v[72:73], v[42:45], off offset:64
	v_lshl_add_u64 v[46:47], v[58:59], 2, v[60:61]
	s_nop 0
	s_waitcnt vmcnt(4)
	v_pk_fma_f32 v[38:39], v[38:39], v[212:213], v[208:209]
	v_pk_fma_f32 v[40:41], v[40:41], v[214:215], v[210:211]
	global_store_dwordx4 v[72:73], v[38:41], off offset:128
	v_lshl_add_u64 v[42:43], v[54:55], 2, v[60:61]
	s_nop 0
	s_waitcnt vmcnt(3)
	v_pk_fma_f32 v[34:35], v[34:35], v[220:221], v[216:217]
	v_pk_fma_f32 v[36:37], v[36:37], v[222:223], v[218:219]
	global_store_dwordx4 v[72:73], v[34:37], off offset:192
	v_mov_b64_e32 v[38:39], s[12:13]
	s_nop 0
	v_mul_hi_i32 v34, v0, s59
	v_lshrrev_b32_e32 v35, 31, v34
	v_ashrrev_i32_e32 v34, 9, v34
	v_add_u32_e32 v40, v34, v35
	v_mul_i32_i24_e32 v34, 0x900, v40
	v_sub_u32_e32 v34, v0, v34
	v_cmp_lt_i32_e32 vcc, s24, v34
	v_mov_b64_e32 v[36:37], s[42:43]
	s_and_saveexec_b64 s[40:41], vcc
	s_xor_b64 s[40:41], exec, s[40:41]
	s_cbranch_execz .LBB0_1070
	v_readlane_b32 s12, v240, 41
	v_add_u32_e32 v0, 0xffffff00, v34
	v_readlane_b32 s13, v240, 42
	v_mov_b64_e32 v[36:37], s[76:77]
	v_mov_b64_e32 v[34:35], v[0:1]
	v_mov_b64_e32 v[38:39], s[12:13]
.LBB0_1070:
	s_or_saveexec_b64 s[40:41], s[40:41]
	v_add_u32_e32 v40, s44, v40
	v_ashrrev_i32_e32 v41, 31, v40
	v_mov_b64_e32 v[44:45], 21
	v_mov_b64_e32 v[42:43], v[40:41]
	s_xor_b64 exec, exec, s[40:41]
	v_ashrrev_i32_e32 v35, 31, v34
	v_mov_b64_e32 v[42:43], 16
	v_mov_b64_e32 v[44:45], 18
	s_or_b64 exec, exec, s[40:41]
	v_lshlrev_b64 v[40:41], v44, v[40:41]
	v_lshlrev_b64 v[34:35], 10, v[34:35]
	v_lshl_add_u64 v[34:35], v[40:41], 0, v[34:35]
	v_readlane_b32 s12, v240, 35
	v_lshlrev_b64 v[34:35], 2, v[34:35]
	v_readlane_b32 s13, v240, 36
	v_lshl_add_u64 v[38:39], v[38:39], 0, v[34:35]
	v_lshl_add_u64 v[34:35], v[36:37], 0, v[34:35]
	v_lshl_add_u64 v[36:37], v[42:43], 0, s[12:13]
	v_mov_b64_e32 v[40:41], s[90:91]
	v_mad_u64_u32 v[40:41], s[40:41], v36, s14, v[40:41]
	v_mad_i32_i24 v41, v37, s14, v41
	s_mov_b64 s[12:13], 0x2000
	v_lshl_add_u64 v[42:43], v[40:41], 0, s[12:13]
	v_lshl_add_u64 v[44:45], v[38:39], 0, v[66:67]
	v_lshl_add_u64 v[38:39], v[42:43], 0, v[66:67]
	v_lshl_add_u64 v[46:47], v[34:35], 0, v[66:67]
	global_load_dwordx4 v[34:37], v[44:45], off
	s_nop 0
	v_mov_b64_e32 v[232:233], v[38:39]
	global_load_dwordx4 v[38:41], v[38:39], off
	global_load_dwordx4 v[200:203], v[44:45], off offset:64
	global_load_dwordx4 v[204:207], v[232:233], off offset:64
	global_load_dwordx4 v[208:211], v[44:45], off offset:128
	global_load_dwordx4 v[212:215], v[232:233], off offset:128
	global_load_dwordx4 v[216:219], v[44:45], off offset:192
	global_load_dwordx4 v[220:223], v[232:233], off offset:192
	v_or_b32_e32 v0, 48, v78
	v_readlane_b32 s40, v240, 6
	v_readlane_b32 s12, v241, 62
	v_readlane_b32 s42, v240, 8
	v_readlane_b32 s43, v240, 9
	v_readlane_b32 s13, v241, 63
	v_readlane_b32 s41, v240, 7
	s_waitcnt vmcnt(6)
	v_pk_fma_f32 v[30:31], v[30:31], v[38:39], v[34:35]
	v_pk_fma_f32 v[32:33], v[32:33], v[40:41], v[36:37]
	global_store_dwordx4 v[46:47], v[30:33], off
	v_lshl_add_u64 v[34:35], v[62:63], 2, v[42:43]
	s_nop 0
	s_waitcnt vmcnt(5)
	v_pk_fma_f32 v[26:27], v[26:27], v[204:205], v[200:201]
	v_pk_fma_f32 v[28:29], v[28:29], v[206:207], v[202:203]
	global_store_dwordx4 v[46:47], v[26:29], off offset:64
	v_lshl_add_u64 v[30:31], v[58:59], 2, v[42:43]
	s_nop 0
	s_waitcnt vmcnt(4)
	v_pk_fma_f32 v[22:23], v[22:23], v[212:213], v[208:209]
	v_pk_fma_f32 v[24:25], v[24:25], v[214:215], v[210:211]
	global_store_dwordx4 v[46:47], v[22:25], off offset:128
	v_lshl_add_u64 v[26:27], v[54:55], 2, v[42:43]
	s_nop 0
	s_waitcnt vmcnt(3)
	v_pk_fma_f32 v[18:19], v[18:19], v[220:221], v[216:217]
	v_pk_fma_f32 v[20:21], v[20:21], v[222:223], v[218:219]
	global_store_dwordx4 v[46:47], v[18:21], off offset:192
	v_mov_b64_e32 v[22:23], s[12:13]
	s_nop 0
	v_mul_hi_i32 v18, v0, s59
	v_lshrrev_b32_e32 v19, 31, v18
	v_ashrrev_i32_e32 v18, 9, v18
	v_add_u32_e32 v24, v18, v19
	v_mul_i32_i24_e32 v18, 0x900, v24
	v_sub_u32_e32 v18, v0, v18
	v_cmp_lt_i32_e32 vcc, s24, v18
	v_mov_b64_e32 v[20:21], s[42:43]
	s_and_saveexec_b64 s[40:41], vcc
	s_xor_b64 s[40:41], exec, s[40:41]
	s_cbranch_execz .LBB0_1074
	v_readlane_b32 s12, v240, 41
	v_add_u32_e32 v0, 0xffffff00, v18
	v_readlane_b32 s13, v240, 42
	v_mov_b64_e32 v[20:21], s[76:77]
	v_mov_b64_e32 v[18:19], v[0:1]
	v_mov_b64_e32 v[22:23], s[12:13]
